# write-through (sc1) on the 16-byte output stores of phases 0, 11 and the weight-conversion stores of phases 6 and 14, so the following grid barriers find a cleaner L2
# baseline (speedup 1.0000x reference)
.LBB0_71:
	v_and_b32_e32 v17, 60, v15
	v_add_u32_e32 v18, 48, v15
	v_add_u32_e32 v30, s4, v16
	v_add_u32_e32 v31, v10, v15
	v_add_u32_e32 v32, v13, v15
	v_add_u32_e32 v33, v14, v15
	v_lshl_add_u32 v17, v17, 2, 0
	v_and_b32_e32 v34, 60, v18
	ds_read_b128 v[18:21], v30 offset:1024
	ds_read_b128 v[22:25], v30 offset:2048
	ds_read_b128 v[26:29], v30 offset:3072
	v_and_b32_e32 v35, 63, v31
	v_add_u32_e32 v36, 48, v31
	v_and_b32_e32 v37, 62, v32
	v_add_u32_e32 v38, 48, v32
	v_and_b32_e32 v39, 63, v33
	v_add_u32_e32 v40, 48, v33
	ds_read_b128 v[30:33], v30
	v_lshl_add_u32 v41, v34, 2, 0
	v_and_b32_e32 v42, 63, v36
	ds_read_b32 v34, v17
	ds_read_b32 v36, v41
	v_and_b32_e32 v38, 62, v38
	v_lshl_add_u32 v39, v39, 2, 0
	v_and_b32_e32 v40, 63, v40
	v_lshl_add_u32 v35, v35, 2, 0
	v_lshl_add_u32 v37, v37, 2, 0
	v_lshl_add_u32 v17, v42, 2, 0
	v_lshl_add_u32 v41, v38, 2, 0
	v_lshl_add_u32 v43, v40, 2, 0
	ds_read_b32 v38, v39
	ds_read_b32 v40, v35
	ds_read_b32 v42, v37
	ds_read_b32 v44, v17
	ds_read_b32 v46, v43
	ds_read_b32 v48, v41
	s_waitcnt lgkmcnt(11)
	v_mov_b32_e32 v51, v18
	s_waitcnt lgkmcnt(10)
	v_mov_b32_e32 v52, v22
	s_waitcnt lgkmcnt(9)
	v_mov_b32_e32 v53, v26
	s_waitcnt lgkmcnt(8)
	v_mov_b32_e32 v50, v30
	v_mov_b32_e32 v26, v23
	v_mov_b32_e32 v18, v31
	s_waitcnt lgkmcnt(7)
	v_pk_fma_f32 v[4:5], v[34:35], v[52:53], v[4:5] op_sel_hi:[0,1,1]
	v_pk_fma_f32 v[2:3], v[34:35], v[50:51], v[2:3] op_sel_hi:[0,1,1]
	s_waitcnt lgkmcnt(6)
	v_pk_fma_f32 v[8:9], v[36:37], v[52:53], v[8:9] op_sel_hi:[0,1,1]
	v_pk_fma_f32 v[6:7], v[36:37], v[50:51], v[6:7] op_sel_hi:[0,1,1]
	v_mov_b32_e32 v23, v20
	v_mov_b32_e32 v54, v24
	v_mov_b32_e32 v55, v28
	v_mov_b32_e32 v22, v32
	s_waitcnt lgkmcnt(4)
	v_pk_fma_f32 v[4:5], v[40:41], v[26:27], v[4:5] op_sel_hi:[0,1,1]
	v_pk_fma_f32 v[2:3], v[40:41], v[18:19], v[2:3] op_sel_hi:[0,1,1]
	s_waitcnt lgkmcnt(2)
	v_pk_fma_f32 v[8:9], v[44:45], v[26:27], v[8:9] op_sel_hi:[0,1,1]
	v_pk_fma_f32 v[6:7], v[44:45], v[18:19], v[6:7] op_sel_hi:[0,1,1]
	s_add_i32 s4, s4, 16
	v_mov_b32_e32 v28, v25
	v_mov_b32_e32 v20, v33
	v_pk_fma_f32 v[4:5], v[42:43], v[54:55], v[4:5] op_sel_hi:[0,1,1]
	v_pk_fma_f32 v[2:3], v[42:43], v[22:23], v[2:3] op_sel_hi:[0,1,1]
	s_waitcnt lgkmcnt(0)
	v_pk_fma_f32 v[8:9], v[48:49], v[54:55], v[8:9] op_sel_hi:[0,1,1]
	v_pk_fma_f32 v[6:7], v[48:49], v[22:23], v[6:7] op_sel_hi:[0,1,1]
	v_add_u32_e32 v15, v15, v12
	s_cmpk_lg_i32 s4, 0x100
	v_pk_fma_f32 v[4:5], v[38:39], v[28:29], v[4:5] op_sel_hi:[0,1,1]
	v_pk_fma_f32 v[2:3], v[38:39], v[20:21], v[2:3] op_sel_hi:[0,1,1]
	v_pk_fma_f32 v[8:9], v[46:47], v[28:29], v[8:9] op_sel_hi:[0,1,1]
	v_pk_fma_f32 v[6:7], v[46:47], v[20:21], v[6:7] op_sel_hi:[0,1,1]
	s_cbranch_scc1 .LBB0_71
	s_load_dwordx16 s[72:87], s[0:1], 0xc0
	v_cvt_pk_bf16_f32 v2, v2, v3
	v_cvt_pk_bf16_f32 v3, v4, v5
	v_cvt_pk_bf16_f32 v4, v6, v7
	v_lshlrev_b32_e32 v6, 11, v10
	v_and_b32_e32 v62, 0x7f800, v6
	v_cvt_pk_bf16_f32 v5, v8, v9
	s_waitcnt lgkmcnt(0)
	v_lshl_add_u64 v[6:7], s[74:75], 0, v[62:63]
	v_lshlrev_b32_e32 v8, 2, v11
	v_ashrrev_i32_e32 v9, 31, v8
	v_lshl_add_u64 v[6:7], s[14:15], 1, v[6:7]
	v_lshl_add_u64 v[6:7], v[8:9], 1, v[6:7]
	v_add_co_u32_e32 v8, vcc, 0x480000, v6
	s_mov_b64 s[4:5], 0
	s_nop 0
	v_addc_co_u32_e32 v9, vcc, 0, v7, vcc
	global_store_dwordx2 v[8:9], v[2:3], off sc1
	v_add_co_u32_e32 v2, vcc, 0x500000, v6
	s_nop 1
	v_addc_co_u32_e32 v3, vcc, 0, v7, vcc
	global_store_dwordx2 v[2:3], v[4:5], off sc1

.LBB0_75:
	s_or_b64 exec, exec, s[6:7]
	v_mul_f32_e32 v8, v12, v12
	v_fmamk_f32 v9, v8, 0xb94c1982, v75
	v_fmaak_f32 v9, v8, v9, 0xbe2aaa9d
	v_mul_f32_e32 v9, v8, v9
	v_fmac_f32_e32 v12, v12, v9
	v_fmamk_f32 v9, v8, 0x37d75334, v84
	v_fmaak_f32 v9, v8, v9, 0x3d2aabf7
	v_fmaak_f32 v9, v8, v9, 0xbf000004
	v_fma_f32 v8, v8, v9, 1.0
	v_and_b32_e32 v9, 1, v11
	v_cmp_eq_u32_e64 s[6:7], 0, v9
	v_lshlrev_b32_e32 v9, 30, v11
	v_and_b32_e32 v9, 0x80000000, v9
	v_xor_b32_e32 v6, v7, v6
	v_cndmask_b32_e64 v8, v8, v12, s[6:7]
	v_xor_b32_e32 v6, v6, v9
	v_xor_b32_e32 v6, v6, v8
	v_cndmask_b32_e32 v6, v86, v6, vcc
	v_add_co_u32_e32 v5, vcc, 0x200, v5
	s_xor_b64 s[6:7], vcc, -1
	s_and_b64 s[6:7], exec, s[6:7]
	global_store_dword v[2:3], v6, off sc1
	v_lshl_add_u64 v[2:3], v[2:3], 0, s[22:23]
	s_or_b64 s[4:5], s[6:7], s[4:5]
	v_add_u32_e32 v4, 32, v4
	s_andn2_b64 exec, exec, s[4:5]
	s_cbranch_execz .LBB0_84

.LBB0_78:
	s_or_saveexec_b64 s[6:7], s[38:39]
	s_mov_b32 s8, 0x3f22f983
	v_mul_f32_e64 v10, |v6|, s8
	v_rndne_f32_e32 v10, v10
	s_xor_b64 exec, exec, s[6:7]
	v_cvt_i32_f32_e32 v11, v10
	v_fma_f32 v12, v10, s61, |v6|
	v_fmac_f32_e32 v12, 0xb3a22168, v10
	v_fmac_f32_e32 v12, 0xa7c234c4, v10
	s_or_b64 exec, exec, s[6:7]
	v_mul_f32_e32 v13, v12, v12
	v_fmamk_f32 v14, v13, 0xb94c1982, v75
	v_fmaak_f32 v14, v13, v14, 0xbe2aaa9d
	v_mul_f32_e32 v14, v13, v14
	v_fmac_f32_e32 v12, v12, v14
	v_fmamk_f32 v14, v13, 0x37d75334, v84
	v_fmaak_f32 v14, v13, v14, 0x3d2aabf7
	v_fmaak_f32 v14, v13, v14, 0xbf000004
	v_fma_f32 v13, v13, v14, 1.0
	v_and_b32_e32 v14, 1, v11
	v_cmp_eq_u32_e32 vcc, 0, v14
	v_lshlrev_b32_e32 v11, 30, v11
	s_brev_b32 s6, 1
	v_cndmask_b32_e64 v12, -v12, v13, vcc
	v_bitop3_b32 v11, v11, v12, s6 bitop3:0x6c
	v_cmp_class_f32_e64 vcc, v6, s19
	s_nop 1
	v_cndmask_b32_e32 v11, v86, v11, vcc
	global_store_dword v[2:3], v11, off offset:-4096 sc1
	s_and_saveexec_b64 s[6:7], s[12:13]
	s_xor_b64 s[38:39], exec, s[6:7]
	s_cbranch_execz .LBB0_82
	v_cmp_lt_u32_e64 s[6:7], 63, v9
	s_nop 1
	v_cndmask_b32_e64 v10, 0, v87, s[6:7]
	v_add_u32_e32 v9, v10, v9
	v_cmp_lt_u32_e64 s[8:9], 31, v9
	s_nop 1
	v_cndmask_b32_e64 v10, 0, v88, s[8:9]
	v_add_u32_e32 v9, v10, v9
	v_cmp_lt_u32_e64 s[10:11], 31, v9
	s_nop 1
	v_cndmask_b32_e64 v10, 0, v88, s[10:11]
	v_add_u32_e32 v22, v10, v9
	v_mad_u64_u32 v[10:11], s[12:13], v8, s27, 0
	v_mov_b32_e32 v62, v11
	v_mad_u64_u32 v[12:13], s[12:13], v8, s29, v[62:63]
	v_mov_b32_e32 v62, v13
	v_mad_u64_u32 v[14:15], s[12:13], v8, s31, v[62:63]
	v_mov_b32_e32 v62, v15
	v_mad_u64_u32 v[16:17], s[12:13], v8, s35, v[62:63]
	v_mov_b32_e32 v62, v17
	v_mad_u64_u32 v[18:19], s[12:13], v8, s37, v[62:63]
	v_mov_b32_e32 v62, v19
	v_mad_u64_u32 v[20:21], s[12:13], v8, s58, v[62:63]
	v_mov_b32_e32 v62, v21
	v_mad_u64_u32 v[8:9], s[12:13], v8, s59, v[62:63]
	v_cndmask_b32_e64 v11, v20, v16, s[6:7]
	v_cndmask_b32_e64 v8, v8, v18, s[6:7]
	v_cndmask_b32_e64 v9, v9, v20, s[6:7]
	v_cndmask_b32_e64 v13, v8, v11, s[8:9]
	v_cndmask_b32_e64 v8, v9, v8, s[8:9]
	v_cndmask_b32_e64 v9, v18, v14, s[6:7]
	v_cndmask_b32_e64 v11, v11, v9, s[8:9]
	v_cndmask_b32_e64 v12, v16, v12, s[6:7]
	v_cndmask_b32_e64 v8, v8, v13, s[10:11]
	v_cndmask_b32_e64 v13, v13, v11, s[10:11]
	v_sub_u32_e32 v15, 32, v22
	v_cndmask_b32_e64 v9, v9, v12, s[8:9]
	v_alignbit_b32 v17, v8, v13, v15
	v_cmp_eq_u32_e64 s[12:13], 0, v22
	v_cndmask_b32_e64 v11, v11, v9, s[10:11]
	v_alignbit_b32 v16, v13, v11, v15
	v_cndmask_b32_e64 v8, v17, v8, s[12:13]
	v_cndmask_b32_e64 v10, v14, v10, s[6:7]
	v_cndmask_b32_e64 v13, v16, v13, s[12:13]
	v_bfe_u32 v18, v8, 29, 1
	v_cndmask_b32_e64 v10, v12, v10, s[8:9]
	v_alignbit_b32 v16, v8, v13, 30
	v_sub_u32_e32 v19, 0, v18
	v_cndmask_b32_e64 v9, v9, v10, s[10:11]
	v_xor_b32_e32 v16, v16, v19
	v_alignbit_b32 v10, v11, v9, v15
	v_cndmask_b32_e64 v10, v10, v11, s[12:13]
	v_ffbh_u32_e32 v12, v16
	v_alignbit_b32 v11, v13, v10, 30
	v_min_u32_e32 v12, 32, v12
	v_alignbit_b32 v9, v10, v9, 30
	v_xor_b32_e32 v11, v11, v19
	v_sub_u32_e32 v13, 31, v12
	v_xor_b32_e32 v9, v9, v19
	v_alignbit_b32 v14, v16, v11, v13
	v_alignbit_b32 v9, v11, v9, v13
	v_alignbit_b32 v10, v14, v9, 9
	v_ffbh_u32_e32 v11, v10
	v_min_u32_e32 v11, 32, v11
	v_lshrrev_b32_e32 v17, 29, v8
	v_not_b32_e32 v13, v11
	v_alignbit_b32 v9, v10, v9, v13
	v_lshlrev_b32_e32 v10, 31, v17
	v_or_b32_e32 v13, 0x33000000, v10
	v_add_lshl_u32 v11, v11, v12, 23
	v_lshrrev_b32_e32 v9, 9, v9
	v_sub_u32_e32 v11, v13, v11
	v_or_b32_e32 v10, 0.5, v10
	v_lshlrev_b32_e32 v12, 23, v12
	v_or_b32_e32 v9, v11, v9
	v_lshrrev_b32_e32 v11, 9, v14
	v_sub_u32_e32 v10, v10, v12
	v_or_b32_e32 v10, v11, v10
	v_mul_f32_e32 v11, 0x3fc90fda, v10
	v_fma_f32 v12, v10, s60, -v11
	v_fmac_f32_e32 v12, 0x33a22168, v10
	v_fmac_f32_e32 v12, 0x3fc90fda, v9
	v_lshrrev_b32_e32 v8, 30, v8
	v_add_f32_e32 v12, v11, v12
	v_add_u32_e32 v11, v18, v8

.LBB0_99:
	s_or_b64 exec, exec, s[4:5]
	s_add_i32 s5, s71, 0xfffffe80
	s_lshl_b32 s4, s5, 3
	v_lshlrev_b32_e32 v2, 3, v2
	v_mul_lo_u32 v4, v2, s4
	v_add_u32_e32 v6, s4, v4
	v_and_b32_e32 v7, 0xff8, v6
	v_add_u32_e32 v8, 0x400, v6
	v_add_u32_e32 v6, s4, v6
	v_add_u32_e32 v11, s4, v6
	v_and_b32_e32 v5, 0xfc0, v4
	v_add_u32_e32 v4, 0x400, v4
	v_add_u32_e32 v12, 0x400, v11
	v_and_b32_e32 v4, 0xfc0, v4
	v_and_b32_e32 v8, 0xff8, v8
	v_and_b32_e32 v9, 0xff0, v6
	v_add_u32_e32 v6, 0x400, v6
	v_and_b32_e32 v12, 0xff8, v12
	v_lshl_add_u32 v5, v5, 2, 0
	v_lshl_add_u32 v7, v7, 2, 0
	v_lshl_add_u32 v4, v4, 2, 0
	v_lshl_add_u32 v8, v8, 2, 0
	v_and_b32_e32 v10, 0xff8, v11
	v_lshl_add_u32 v9, v9, 2, 0
	v_and_b32_e32 v6, 0xff0, v6
	v_lshl_add_u32 v12, v12, 2, 0
	s_waitcnt lgkmcnt(0)
	s_barrier
	v_lshl_add_u32 v10, v10, 2, 0
	v_lshl_add_u32 v6, v6, 2, 0
	ds_read_b32 v5, v5
	ds_read_b32 v7, v7
	ds_read_b32 v4, v4
	ds_read_b32 v8, v8
	ds_read_b32 v9, v9
	ds_read_b32 v13, v10
	ds_read_b32 v14, v6
	ds_read_b32 v12, v12
	s_waitcnt lgkmcnt(4)
	v_cvt_pk_bf16_f32 v10, v4, v8
	v_add_u32_e32 v4, s4, v11
	v_add_u32_e32 v8, s4, v4
	v_cvt_pk_bf16_f32 v6, v5, v7
	s_waitcnt lgkmcnt(2)
	v_cvt_pk_bf16_f32 v7, v9, v13
	v_and_b32_e32 v9, 0xff8, v8
	v_add_u32_e32 v11, 0x400, v8
	v_add_u32_e32 v8, s4, v8
	v_add_u32_e32 v15, s4, v8
	v_and_b32_e32 v5, 0xfe0, v4
	v_add_u32_e32 v4, 0x400, v4
	v_and_b32_e32 v16, 0xff8, v15
	v_add_u32_e32 v15, 0x400, v15
	v_and_b32_e32 v4, 0xfe0, v4
	v_and_b32_e32 v13, 0xff0, v8
	v_add_u32_e32 v8, 0x400, v8
	v_and_b32_e32 v15, 0xff8, v15
	s_load_dwordx16 s[72:87], s[0:1], 0xc0
	v_lshl_add_u32 v5, v5, 2, 0
	v_lshl_add_u32 v9, v9, 2, 0
	v_lshl_add_u32 v4, v4, 2, 0
	v_and_b32_e32 v11, 0xff8, v11
	v_lshl_add_u32 v13, v13, 2, 0
	v_lshl_add_u32 v16, v16, 2, 0
	v_and_b32_e32 v8, 0xff0, v8
	v_lshl_add_u32 v15, v15, 2, 0
	v_lshl_add_u32 v11, v11, 2, 0
	v_lshl_add_u32 v8, v8, 2, 0
	ds_read_b32 v5, v5
	ds_read_b32 v9, v9
	ds_read_b32 v4, v4
	ds_read_b32 v17, v11
	ds_read_b32 v13, v13
	ds_read_b32 v16, v16
	ds_read_b32 v18, v8
	ds_read_b32 v15, v15
	s_lshl_b32 s5, s5, 17
	v_ashrrev_i32_e32 v3, 31, v2
	s_waitcnt lgkmcnt(0)
	s_add_u32 s6, s86, s5
	v_cvt_pk_bf16_f32 v11, v14, v12
	v_cvt_pk_bf16_f32 v8, v5, v9
	v_cvt_pk_bf16_f32 v12, v4, v17
	s_addc_u32 s7, s87, 0
	v_lshlrev_b64 v[4:5], 1, v[2:3]
	v_cvt_pk_bf16_f32 v9, v13, v16
	v_cvt_pk_bf16_f32 v13, v18, v15
	v_lshl_add_u64 v[14:15], s[6:7], 0, v[4:5]
	global_store_dwordx4 v[14:15], v[6:9], off sc1
	s_or_b32 s5, s4, 1
	v_mul_lo_u32 v3, v2, s5
	v_add_co_u32_e32 v6, vcc, s21, v14
	s_nop 1
	v_addc_co_u32_e32 v7, vcc, 0, v15, vcc
	global_store_dwordx4 v[6:7], v[10:13], off sc1
	v_add_u32_e32 v7, s5, v3
	v_and_b32_e32 v8, 0xff9, v7
	v_add_u32_e32 v9, 0x400, v7
	v_add_u32_e32 v7, s5, v7
	v_add_u32_e32 v11, s5, v7
	v_and_b32_e32 v6, 0xff8, v3
	v_add_u32_e32 v3, 0x400, v3
	v_add_u32_e32 v13, 0x400, v11
	v_and_b32_e32 v3, 0xff8, v3
	v_and_b32_e32 v9, 0xff9, v9
	v_and_b32_e32 v10, 0xffa, v7
	v_and_b32_e32 v12, 0xffb, v11
	v_add_u32_e32 v7, 0x400, v7
	v_and_b32_e32 v13, 0xffb, v13
	v_lshl_add_u32 v6, v6, 2, 0
	v_lshl_add_u32 v8, v8, 2, 0
	v_lshl_add_u32 v3, v3, 2, 0
	v_lshl_add_u32 v9, v9, 2, 0
	v_lshl_add_u32 v12, v12, 2, 0
	v_and_b32_e32 v7, 0xffa, v7
	v_lshl_add_u32 v13, v13, 2, 0
	v_lshl_add_u32 v10, v10, 2, 0
	v_lshl_add_u32 v7, v7, 2, 0
	ds_read_b32 v6, v6
	ds_read_b32 v8, v8
	ds_read_b32 v3, v3
	ds_read_b32 v9, v9
	ds_read_b32 v14, v10
	ds_read_b32 v12, v12
	ds_read_b32 v15, v7
	ds_read_b32 v13, v13
	s_waitcnt lgkmcnt(4)
	v_cvt_pk_bf16_f32 v10, v3, v9
	v_add_u32_e32 v3, s5, v11
	v_add_u32_e32 v9, s5, v3
	s_waitcnt lgkmcnt(2)
	v_cvt_pk_bf16_f32 v7, v14, v12
	v_and_b32_e32 v11, 0xffd, v9
	v_add_u32_e32 v12, 0x400, v9
	v_add_u32_e32 v9, s5, v9
	v_add_u32_e32 v16, s5, v9
	v_cvt_pk_bf16_f32 v6, v6, v8
	v_and_b32_e32 v8, 0xffc, v3
	v_add_u32_e32 v3, 0x400, v3
	v_and_b32_e32 v17, 0xfff, v16
	v_add_u32_e32 v16, 0x400, v16
	v_and_b32_e32 v3, 0xffc, v3
	v_and_b32_e32 v12, 0xffd, v12
	v_and_b32_e32 v14, 0xffe, v9
	v_add_u32_e32 v9, 0x400, v9
	v_and_b32_e32 v16, 0xfff, v16
	v_lshl_add_u32 v8, v8, 2, 0
	v_lshl_add_u32 v3, v3, 2, 0
	v_lshl_add_u32 v12, v12, 2, 0
	v_lshl_add_u32 v14, v14, 2, 0
	v_lshl_add_u32 v17, v17, 2, 0
	v_and_b32_e32 v9, 0xffe, v9
	v_lshl_add_u32 v16, v16, 2, 0
	v_lshl_add_u32 v11, v11, 2, 0
	v_lshl_add_u32 v9, v9, 2, 0
	ds_read_b32 v8, v8
	ds_read_b32 v18, v11
	ds_read_b32 v3, v3
	ds_read_b32 v12, v12
	ds_read_b32 v14, v14
	ds_read_b32 v17, v17
	ds_read_b32 v19, v9
	ds_read_b32 v16, v16
	s_lshl_b32 s5, s5, 14
	s_add_u32 s6, s86, s5
	s_addc_u32 s7, s87, 0
	s_waitcnt lgkmcnt(8)
	v_cvt_pk_bf16_f32 v11, v15, v13
	s_waitcnt lgkmcnt(6)
	v_cvt_pk_bf16_f32 v8, v8, v18
	s_waitcnt lgkmcnt(2)
	v_cvt_pk_bf16_f32 v9, v14, v17
	v_lshl_add_u64 v[14:15], s[6:7], 0, v[4:5]
	global_store_dwordx4 v[14:15], v[6:9], off sc1
	s_or_b32 s5, s4, 2
	v_cvt_pk_bf16_f32 v12, v3, v12
	v_add_co_u32_e32 v6, vcc, s21, v14
	s_waitcnt lgkmcnt(0)
	v_cvt_pk_bf16_f32 v13, v19, v16
	v_addc_co_u32_e32 v7, vcc, 0, v15, vcc
	v_mul_lo_u32 v3, v2, s5
	global_store_dwordx4 v[6:7], v[10:13], off sc1
	v_add_u32_e32 v7, s5, v3
	v_and_b32_e32 v8, 0xffa, v7
	v_add_u32_e32 v9, 0x400, v7
	v_add_u32_e32 v7, s5, v7
	v_add_u32_e32 v11, s5, v7
	v_and_b32_e32 v6, 0xff0, v3
	v_add_u32_e32 v3, 0x400, v3
	v_add_u32_e32 v13, 0x400, v11
	v_and_b32_e32 v3, 0xff0, v3
	v_and_b32_e32 v9, 0xffa, v9
	v_and_b32_e32 v10, 0xff4, v7
	v_and_b32_e32 v12, 0xffe, v11
	v_add_u32_e32 v7, 0x400, v7
	v_and_b32_e32 v13, 0xffe, v13
	v_lshl_add_u32 v6, v6, 2, 0
	v_lshl_add_u32 v8, v8, 2, 0
	v_lshl_add_u32 v3, v3, 2, 0
	v_lshl_add_u32 v9, v9, 2, 0
	v_lshl_add_u32 v12, v12, 2, 0
	v_and_b32_e32 v7, 0xff4, v7
	v_lshl_add_u32 v13, v13, 2, 0
	v_lshl_add_u32 v10, v10, 2, 0
	v_lshl_add_u32 v7, v7, 2, 0
	ds_read_b32 v6, v6
	ds_read_b32 v8, v8
	ds_read_b32 v3, v3
	ds_read_b32 v9, v9
	ds_read_b32 v14, v10
	ds_read_b32 v12, v12
	ds_read_b32 v15, v7
	ds_read_b32 v13, v13
	s_waitcnt lgkmcnt(4)
	v_cvt_pk_bf16_f32 v10, v3, v9
	v_add_u32_e32 v3, s5, v11
	v_add_u32_e32 v9, s5, v3
	s_waitcnt lgkmcnt(2)
	v_cvt_pk_bf16_f32 v7, v14, v12
	v_and_b32_e32 v11, 0xffa, v9
	v_add_u32_e32 v12, 0x400, v9
	v_add_u32_e32 v9, s5, v9
	v_add_u32_e32 v16, s5, v9
	v_cvt_pk_bf16_f32 v6, v6, v8
	v_and_b32_e32 v8, 0xff8, v3
	v_add_u32_e32 v3, 0x400, v3
	v_and_b32_e32 v17, 0xffe, v16
	v_add_u32_e32 v16, 0x400, v16
	v_and_b32_e32 v3, 0xff8, v3
	v_and_b32_e32 v12, 0xffa, v12
	v_and_b32_e32 v14, 0xffc, v9
	v_add_u32_e32 v9, 0x400, v9
	v_and_b32_e32 v16, 0xffe, v16
	v_lshl_add_u32 v8, v8, 2, 0
	v_lshl_add_u32 v3, v3, 2, 0
	v_lshl_add_u32 v12, v12, 2, 0
	v_lshl_add_u32 v14, v14, 2, 0
	v_lshl_add_u32 v17, v17, 2, 0
	v_and_b32_e32 v9, 0xffc, v9
	v_lshl_add_u32 v16, v16, 2, 0
	v_lshl_add_u32 v11, v11, 2, 0
	v_lshl_add_u32 v9, v9, 2, 0
	ds_read_b32 v8, v8
	ds_read_b32 v18, v11
	ds_read_b32 v3, v3
	ds_read_b32 v12, v12
	ds_read_b32 v14, v14
	ds_read_b32 v17, v17
	ds_read_b32 v19, v9
	ds_read_b32 v16, v16
	s_lshl_b32 s5, s5, 14
	s_add_u32 s6, s86, s5
	s_addc_u32 s7, s87, 0
	s_waitcnt lgkmcnt(8)
	v_cvt_pk_bf16_f32 v11, v15, v13
	s_waitcnt lgkmcnt(6)
	v_cvt_pk_bf16_f32 v8, v8, v18
	s_waitcnt lgkmcnt(2)
	v_cvt_pk_bf16_f32 v9, v14, v17
	v_lshl_add_u64 v[14:15], s[6:7], 0, v[4:5]
	global_store_dwordx4 v[14:15], v[6:9], off sc1
	s_or_b32 s5, s4, 3
	v_cvt_pk_bf16_f32 v12, v3, v12
	v_add_co_u32_e32 v6, vcc, s21, v14
	s_waitcnt lgkmcnt(0)
	v_cvt_pk_bf16_f32 v13, v19, v16
	v_addc_co_u32_e32 v7, vcc, 0, v15, vcc
	v_mul_lo_u32 v3, v2, s5
	global_store_dwordx4 v[6:7], v[10:13], off sc1
	v_add_u32_e32 v7, s5, v3
	v_and_b32_e32 v8, 0xffb, v7
	v_add_u32_e32 v9, 0x400, v7
	v_add_u32_e32 v7, s5, v7
	v_add_u32_e32 v11, s5, v7
	v_and_b32_e32 v6, 0xff8, v3
	v_add_u32_e32 v3, 0x400, v3
	v_add_u32_e32 v13, 0x400, v11
	v_and_b32_e32 v3, 0xff8, v3
	v_and_b32_e32 v9, 0xffb, v9
	v_and_b32_e32 v10, 0xffe, v7
	v_and_b32_e32 v12, 0xff9, v11
	v_add_u32_e32 v7, 0x400, v7
	v_and_b32_e32 v13, 0xff9, v13
	v_lshl_add_u32 v6, v6, 2, 0
	v_lshl_add_u32 v8, v8, 2, 0
	v_lshl_add_u32 v3, v3, 2, 0
	v_lshl_add_u32 v9, v9, 2, 0
	v_lshl_add_u32 v12, v12, 2, 0
	v_and_b32_e32 v7, 0xffe, v7
	v_lshl_add_u32 v13, v13, 2, 0
	v_lshl_add_u32 v10, v10, 2, 0
	v_lshl_add_u32 v7, v7, 2, 0
	ds_read_b32 v6, v6
	ds_read_b32 v8, v8
	ds_read_b32 v3, v3
	ds_read_b32 v9, v9
	ds_read_b32 v14, v10
	ds_read_b32 v12, v12
	ds_read_b32 v15, v7
	ds_read_b32 v13, v13
	s_waitcnt lgkmcnt(4)
	v_cvt_pk_bf16_f32 v10, v3, v9
	v_add_u32_e32 v3, s5, v11
	v_add_u32_e32 v9, s5, v3
	s_waitcnt lgkmcnt(2)
	v_cvt_pk_bf16_f32 v7, v14, v12
	v_and_b32_e32 v11, 0xfff, v9
	v_add_u32_e32 v12, 0x400, v9
	v_add_u32_e32 v9, s5, v9
	v_add_u32_e32 v16, s5, v9
	v_cvt_pk_bf16_f32 v6, v6, v8
	v_and_b32_e32 v8, 0xffc, v3
	v_add_u32_e32 v3, 0x400, v3
	v_and_b32_e32 v17, 0xffd, v16
	v_add_u32_e32 v16, 0x400, v16
	v_and_b32_e32 v3, 0xffc, v3
	v_and_b32_e32 v12, 0xfff, v12
	v_and_b32_e32 v14, 0xffa, v9
	v_add_u32_e32 v9, 0x400, v9
	v_and_b32_e32 v16, 0xffd, v16
	v_lshl_add_u32 v8, v8, 2, 0
	v_lshl_add_u32 v3, v3, 2, 0
	v_lshl_add_u32 v12, v12, 2, 0
	v_lshl_add_u32 v14, v14, 2, 0
	v_lshl_add_u32 v17, v17, 2, 0
	v_and_b32_e32 v9, 0xffa, v9
	v_lshl_add_u32 v16, v16, 2, 0
	v_lshl_add_u32 v11, v11, 2, 0
	v_lshl_add_u32 v9, v9, 2, 0
	ds_read_b32 v8, v8
	ds_read_b32 v18, v11
	ds_read_b32 v3, v3
	ds_read_b32 v12, v12
	ds_read_b32 v14, v14
	ds_read_b32 v17, v17
	ds_read_b32 v19, v9
	ds_read_b32 v16, v16
	s_lshl_b32 s5, s5, 14
	s_add_u32 s6, s86, s5
	s_addc_u32 s7, s87, 0
	s_waitcnt lgkmcnt(8)
	v_cvt_pk_bf16_f32 v11, v15, v13
	s_waitcnt lgkmcnt(6)
	v_cvt_pk_bf16_f32 v8, v8, v18
	s_waitcnt lgkmcnt(2)
	v_cvt_pk_bf16_f32 v9, v14, v17
	v_lshl_add_u64 v[14:15], s[6:7], 0, v[4:5]
	global_store_dwordx4 v[14:15], v[6:9], off sc1
	s_or_b32 s5, s4, 4
	v_cvt_pk_bf16_f32 v12, v3, v12
	v_add_co_u32_e32 v6, vcc, s21, v14
	s_waitcnt lgkmcnt(0)
	v_cvt_pk_bf16_f32 v13, v19, v16
	v_addc_co_u32_e32 v7, vcc, 0, v15, vcc
	v_mul_lo_u32 v3, v2, s5
	global_store_dwordx4 v[6:7], v[10:13], off sc1
	v_add_u32_e32 v7, s5, v3
	v_and_b32_e32 v8, 0xffc, v7
	v_add_u32_e32 v9, 0x400, v7
	v_add_u32_e32 v7, s5, v7
	v_add_u32_e32 v11, s5, v7
	v_and_b32_e32 v6, 0xfe0, v3
	v_add_u32_e32 v3, 0x400, v3
	v_add_u32_e32 v13, 0x400, v11
	v_and_b32_e32 v3, 0xfe0, v3
	v_and_b32_e32 v9, 0xffc, v9
	v_and_b32_e32 v10, 0xff8, v7
	v_and_b32_e32 v12, 0xffc, v11
	v_add_u32_e32 v7, 0x400, v7
	v_and_b32_e32 v13, 0xffc, v13
	v_lshl_add_u32 v6, v6, 2, 0
	v_lshl_add_u32 v8, v8, 2, 0
	v_lshl_add_u32 v3, v3, 2, 0
	v_lshl_add_u32 v9, v9, 2, 0
	v_lshl_add_u32 v12, v12, 2, 0
	v_and_b32_e32 v7, 0xff8, v7
	v_lshl_add_u32 v13, v13, 2, 0
	v_lshl_add_u32 v10, v10, 2, 0
	v_lshl_add_u32 v7, v7, 2, 0
	ds_read_b32 v6, v6
	ds_read_b32 v8, v8
	ds_read_b32 v3, v3
	ds_read_b32 v9, v9
	ds_read_b32 v14, v10
	ds_read_b32 v12, v12
	ds_read_b32 v15, v7
	ds_read_b32 v13, v13
	s_waitcnt lgkmcnt(4)
	v_cvt_pk_bf16_f32 v10, v3, v9
	v_add_u32_e32 v3, s5, v11
	v_add_u32_e32 v9, s5, v3
	s_waitcnt lgkmcnt(2)
	v_cvt_pk_bf16_f32 v7, v14, v12
	v_and_b32_e32 v11, 0xffc, v9
	v_add_u32_e32 v12, 0x400, v9
	v_add_u32_e32 v9, s5, v9
	v_add_u32_e32 v16, s5, v9
	v_cvt_pk_bf16_f32 v6, v6, v8
	v_and_b32_e32 v8, 0xff0, v3
	v_add_u32_e32 v3, 0x400, v3
	v_and_b32_e32 v17, 0xffc, v16
	v_add_u32_e32 v16, 0x400, v16
	v_and_b32_e32 v3, 0xff0, v3
	v_and_b32_e32 v12, 0xffc, v12
	v_and_b32_e32 v14, 0xff8, v9
	v_add_u32_e32 v9, 0x400, v9
	v_and_b32_e32 v16, 0xffc, v16
	v_lshl_add_u32 v8, v8, 2, 0
	v_lshl_add_u32 v3, v3, 2, 0
	v_lshl_add_u32 v12, v12, 2, 0
	v_lshl_add_u32 v14, v14, 2, 0
	v_lshl_add_u32 v17, v17, 2, 0
	v_and_b32_e32 v9, 0xff8, v9
	v_lshl_add_u32 v16, v16, 2, 0
	v_lshl_add_u32 v11, v11, 2, 0
	v_lshl_add_u32 v9, v9, 2, 0
	ds_read_b32 v8, v8
	ds_read_b32 v18, v11
	ds_read_b32 v3, v3
	ds_read_b32 v12, v12
	ds_read_b32 v14, v14
	ds_read_b32 v17, v17
	ds_read_b32 v19, v9
	ds_read_b32 v16, v16
	s_lshl_b32 s5, s5, 14
	s_add_u32 s6, s86, s5
	s_addc_u32 s7, s87, 0
	s_waitcnt lgkmcnt(8)
	v_cvt_pk_bf16_f32 v11, v15, v13
	s_waitcnt lgkmcnt(6)
	v_cvt_pk_bf16_f32 v8, v8, v18
	s_waitcnt lgkmcnt(2)
	v_cvt_pk_bf16_f32 v9, v14, v17
	v_lshl_add_u64 v[14:15], s[6:7], 0, v[4:5]
	global_store_dwordx4 v[14:15], v[6:9], off sc1
	s_or_b32 s5, s4, 5
	v_cvt_pk_bf16_f32 v12, v3, v12
	v_add_co_u32_e32 v6, vcc, s21, v14
	s_waitcnt lgkmcnt(0)
	v_cvt_pk_bf16_f32 v13, v19, v16
	v_addc_co_u32_e32 v7, vcc, 0, v15, vcc
	v_mul_lo_u32 v3, v2, s5
	global_store_dwordx4 v[6:7], v[10:13], off sc1
	v_add_u32_e32 v7, s5, v3
	v_and_b32_e32 v8, 0xffd, v7
	v_add_u32_e32 v9, 0x400, v7
	v_add_u32_e32 v7, s5, v7
	v_add_u32_e32 v11, s5, v7
	v_and_b32_e32 v6, 0xff8, v3
	v_add_u32_e32 v3, 0x400, v3
	v_add_u32_e32 v13, 0x400, v11
	v_and_b32_e32 v3, 0xff8, v3
	v_and_b32_e32 v9, 0xffd, v9
	v_and_b32_e32 v10, 0xffa, v7
	v_and_b32_e32 v12, 0xfff, v11
	v_add_u32_e32 v7, 0x400, v7
	v_and_b32_e32 v13, 0xfff, v13
	v_lshl_add_u32 v6, v6, 2, 0
	v_lshl_add_u32 v8, v8, 2, 0
	v_lshl_add_u32 v3, v3, 2, 0
	v_lshl_add_u32 v9, v9, 2, 0
	v_lshl_add_u32 v12, v12, 2, 0
	v_and_b32_e32 v7, 0xffa, v7
	v_lshl_add_u32 v13, v13, 2, 0
	v_lshl_add_u32 v10, v10, 2, 0
	v_lshl_add_u32 v7, v7, 2, 0
	ds_read_b32 v6, v6
	ds_read_b32 v8, v8
	ds_read_b32 v3, v3
	ds_read_b32 v9, v9
	ds_read_b32 v14, v10
	ds_read_b32 v12, v12
	ds_read_b32 v15, v7
	ds_read_b32 v13, v13
	s_waitcnt lgkmcnt(4)
	v_cvt_pk_bf16_f32 v10, v3, v9
	v_add_u32_e32 v3, s5, v11
	v_add_u32_e32 v9, s5, v3
	s_waitcnt lgkmcnt(2)
	v_cvt_pk_bf16_f32 v7, v14, v12
	v_and_b32_e32 v11, 0xff9, v9
	v_add_u32_e32 v12, 0x400, v9
	v_add_u32_e32 v9, s5, v9
	v_add_u32_e32 v16, s5, v9
	v_cvt_pk_bf16_f32 v6, v6, v8
	v_and_b32_e32 v8, 0xffc, v3
	v_add_u32_e32 v3, 0x400, v3
	v_and_b32_e32 v17, 0xffb, v16
	v_add_u32_e32 v16, 0x400, v16
	v_and_b32_e32 v3, 0xffc, v3
	v_and_b32_e32 v12, 0xff9, v12
	v_and_b32_e32 v14, 0xffe, v9
	v_add_u32_e32 v9, 0x400, v9
	v_and_b32_e32 v16, 0xffb, v16
	v_lshl_add_u32 v8, v8, 2, 0
	v_lshl_add_u32 v3, v3, 2, 0
	v_lshl_add_u32 v12, v12, 2, 0
	v_lshl_add_u32 v14, v14, 2, 0
	v_lshl_add_u32 v17, v17, 2, 0
	v_and_b32_e32 v9, 0xffe, v9
	v_lshl_add_u32 v16, v16, 2, 0
	v_lshl_add_u32 v11, v11, 2, 0
	v_lshl_add_u32 v9, v9, 2, 0
	ds_read_b32 v8, v8
	ds_read_b32 v18, v11
	ds_read_b32 v3, v3
	ds_read_b32 v12, v12
	ds_read_b32 v14, v14
	ds_read_b32 v17, v17
	ds_read_b32 v19, v9
	ds_read_b32 v16, v16
	s_lshl_b32 s5, s5, 14
	s_add_u32 s6, s86, s5
	s_addc_u32 s7, s87, 0
	s_waitcnt lgkmcnt(8)
	v_cvt_pk_bf16_f32 v11, v15, v13
	s_waitcnt lgkmcnt(6)
	v_cvt_pk_bf16_f32 v8, v8, v18
	s_waitcnt lgkmcnt(2)
	v_cvt_pk_bf16_f32 v9, v14, v17
	v_lshl_add_u64 v[14:15], s[6:7], 0, v[4:5]
	global_store_dwordx4 v[14:15], v[6:9], off sc1
	s_or_b32 s5, s4, 6
	v_cvt_pk_bf16_f32 v12, v3, v12
	v_add_co_u32_e32 v6, vcc, s21, v14
	s_waitcnt lgkmcnt(0)
	v_cvt_pk_bf16_f32 v13, v19, v16
	v_addc_co_u32_e32 v7, vcc, 0, v15, vcc
	v_mul_lo_u32 v3, v2, s5
	global_store_dwordx4 v[6:7], v[10:13], off sc1
	v_add_u32_e32 v7, s5, v3
	v_and_b32_e32 v8, 0xffe, v7
	v_add_u32_e32 v9, 0x400, v7
	v_add_u32_e32 v7, s5, v7
	v_add_u32_e32 v11, s5, v7
	v_and_b32_e32 v6, 0xff0, v3
	v_add_u32_e32 v3, 0x400, v3
	v_add_u32_e32 v13, 0x400, v11
	v_and_b32_e32 v3, 0xff0, v3
	v_and_b32_e32 v9, 0xffe, v9
	v_and_b32_e32 v10, 0xffc, v7
	v_and_b32_e32 v12, 0xffa, v11
	v_add_u32_e32 v7, 0x400, v7
	v_and_b32_e32 v13, 0xffa, v13
	v_lshl_add_u32 v6, v6, 2, 0
	v_lshl_add_u32 v8, v8, 2, 0
	v_lshl_add_u32 v3, v3, 2, 0
	v_lshl_add_u32 v9, v9, 2, 0
	v_lshl_add_u32 v12, v12, 2, 0
	v_and_b32_e32 v7, 0xffc, v7
	v_lshl_add_u32 v13, v13, 2, 0
	v_lshl_add_u32 v10, v10, 2, 0
	v_lshl_add_u32 v7, v7, 2, 0
	ds_read_b32 v6, v6
	ds_read_b32 v8, v8
	ds_read_b32 v3, v3
	ds_read_b32 v9, v9
	ds_read_b32 v14, v10
	ds_read_b32 v12, v12
	ds_read_b32 v15, v7
	ds_read_b32 v13, v13
	s_waitcnt lgkmcnt(4)
	v_cvt_pk_bf16_f32 v10, v3, v9
	v_add_u32_e32 v3, s5, v11
	v_add_u32_e32 v9, s5, v3
	s_waitcnt lgkmcnt(2)
	v_cvt_pk_bf16_f32 v7, v14, v12
	v_and_b32_e32 v11, 0xffe, v9
	v_add_u32_e32 v12, 0x400, v9
	v_add_u32_e32 v9, s5, v9
	v_add_u32_e32 v16, s5, v9
	v_cvt_pk_bf16_f32 v6, v6, v8
	v_and_b32_e32 v8, 0xff8, v3
	v_add_u32_e32 v3, 0x400, v3
	v_and_b32_e32 v17, 0xffa, v16
	v_add_u32_e32 v16, 0x400, v16
	v_and_b32_e32 v3, 0xff8, v3
	v_and_b32_e32 v12, 0xffe, v12
	v_and_b32_e32 v14, 0xff4, v9
	v_add_u32_e32 v9, 0x400, v9
	v_and_b32_e32 v16, 0xffa, v16
	v_lshl_add_u32 v8, v8, 2, 0
	v_lshl_add_u32 v3, v3, 2, 0
	v_lshl_add_u32 v12, v12, 2, 0
	v_lshl_add_u32 v14, v14, 2, 0
	v_lshl_add_u32 v17, v17, 2, 0
	v_and_b32_e32 v9, 0xff4, v9
	v_lshl_add_u32 v16, v16, 2, 0
	v_lshl_add_u32 v11, v11, 2, 0
	v_lshl_add_u32 v9, v9, 2, 0
	ds_read_b32 v8, v8
	ds_read_b32 v18, v11
	ds_read_b32 v3, v3
	ds_read_b32 v12, v12
	ds_read_b32 v14, v14
	ds_read_b32 v17, v17
	ds_read_b32 v19, v9
	ds_read_b32 v16, v16
	s_lshl_b32 s5, s5, 14
	s_add_u32 s6, s86, s5
	s_addc_u32 s7, s87, 0
	s_waitcnt lgkmcnt(8)
	v_cvt_pk_bf16_f32 v11, v15, v13
	s_waitcnt lgkmcnt(6)
	v_cvt_pk_bf16_f32 v8, v8, v18
	s_waitcnt lgkmcnt(2)
	v_cvt_pk_bf16_f32 v9, v14, v17
	v_lshl_add_u64 v[14:15], s[6:7], 0, v[4:5]
	global_store_dwordx4 v[14:15], v[6:9], off sc1
	s_or_b32 s4, s4, 7
	v_cvt_pk_bf16_f32 v12, v3, v12
	v_add_co_u32_e32 v6, vcc, s21, v14
	s_waitcnt lgkmcnt(0)
	v_cvt_pk_bf16_f32 v13, v19, v16
	v_addc_co_u32_e32 v7, vcc, 0, v15, vcc
	v_mul_lo_u32 v2, v2, s4
	global_store_dwordx4 v[6:7], v[10:13], off sc1
	v_add_u32_e32 v6, s4, v2
	v_and_b32_e32 v7, 0xfff, v6
	v_add_u32_e32 v8, 0x400, v6
	v_add_u32_e32 v6, s4, v6
	v_add_u32_e32 v11, s4, v6
	v_and_b32_e32 v3, 0xff8, v2
	v_add_u32_e32 v2, 0x400, v2
	v_add_u32_e32 v12, 0x400, v11
	v_and_b32_e32 v2, 0xff8, v2
	v_and_b32_e32 v8, 0xfff, v8
	v_and_b32_e32 v9, 0xffe, v6
	v_add_u32_e32 v6, 0x400, v6
	v_and_b32_e32 v12, 0xffd, v12
	v_lshl_add_u32 v3, v3, 2, 0
	v_lshl_add_u32 v7, v7, 2, 0
	v_lshl_add_u32 v2, v2, 2, 0
	v_lshl_add_u32 v8, v8, 2, 0
	v_and_b32_e32 v10, 0xffd, v11
	v_lshl_add_u32 v9, v9, 2, 0
	v_and_b32_e32 v6, 0xffe, v6
	v_lshl_add_u32 v12, v12, 2, 0
	v_lshl_add_u32 v10, v10, 2, 0
	v_lshl_add_u32 v6, v6, 2, 0
	ds_read_b32 v3, v3
	ds_read_b32 v7, v7
	ds_read_b32 v2, v2
	ds_read_b32 v8, v8
	ds_read_b32 v9, v9
	ds_read_b32 v13, v10
	ds_read_b32 v14, v6
	ds_read_b32 v12, v12
	s_waitcnt lgkmcnt(4)
	v_cvt_pk_bf16_f32 v10, v2, v8
	v_add_u32_e32 v2, s4, v11
	v_add_u32_e32 v8, s4, v2
	v_cvt_pk_bf16_f32 v6, v3, v7
	s_waitcnt lgkmcnt(2)
	v_cvt_pk_bf16_f32 v7, v9, v13
	v_and_b32_e32 v9, 0xffb, v8
	v_add_u32_e32 v11, 0x400, v8
	v_add_u32_e32 v8, s4, v8
	v_add_u32_e32 v15, s4, v8
	v_and_b32_e32 v3, 0xffc, v2
	v_add_u32_e32 v2, 0x400, v2
	v_and_b32_e32 v16, 0xff9, v15
	v_add_u32_e32 v15, 0x400, v15
	v_and_b32_e32 v2, 0xffc, v2
	v_and_b32_e32 v13, 0xffa, v8
	v_add_u32_e32 v8, 0x400, v8
	v_and_b32_e32 v15, 0xff9, v15
	v_lshl_add_u32 v3, v3, 2, 0
	v_lshl_add_u32 v9, v9, 2, 0
	v_lshl_add_u32 v2, v2, 2, 0
	v_and_b32_e32 v11, 0xffb, v11
	v_lshl_add_u32 v13, v13, 2, 0
	v_lshl_add_u32 v16, v16, 2, 0
	v_and_b32_e32 v8, 0xffa, v8
	v_lshl_add_u32 v15, v15, 2, 0
	v_lshl_add_u32 v11, v11, 2, 0
	v_lshl_add_u32 v8, v8, 2, 0
	ds_read_b32 v3, v3
	ds_read_b32 v9, v9
	ds_read_b32 v2, v2
	ds_read_b32 v17, v11
	ds_read_b32 v13, v13
	ds_read_b32 v16, v16
	ds_read_b32 v18, v8
	ds_read_b32 v15, v15
	s_lshl_b32 s4, s4, 14
	s_add_u32 s4, s86, s4
	s_addc_u32 s5, s87, 0
	s_waitcnt lgkmcnt(8)
	v_cvt_pk_bf16_f32 v11, v14, v12
	s_waitcnt lgkmcnt(6)
	v_cvt_pk_bf16_f32 v8, v3, v9
	s_waitcnt lgkmcnt(4)
	v_cvt_pk_bf16_f32 v12, v2, v17
	s_waitcnt lgkmcnt(2)
	v_cvt_pk_bf16_f32 v9, v13, v16
	v_lshl_add_u64 v[2:3], s[4:5], 0, v[4:5]
	global_store_dwordx4 v[2:3], v[6:9], off sc1
	v_add_co_u32_e32 v2, vcc, 0x2000, v2
	s_waitcnt lgkmcnt(0)
	v_cvt_pk_bf16_f32 v13, v18, v15
	v_addc_co_u32_e32 v3, vcc, 0, v3, vcc
	global_store_dwordx4 v[2:3], v[10:13], off sc1

.LBB0_105:
	v_lshl_add_u64 v[82:83], v[76:77], 0, s[8:9]
	v_add_co_u32_e32 v112, vcc, s63, v82
	s_mov_b32 s7, 0xc000
	s_nop 0
	v_addc_co_u32_e32 v113, vcc, 0, v83, vcc
	v_add_co_u32_e32 v114, vcc, s7, v82
	s_mov_b32 s7, 0x12000
	s_nop 0
	v_addc_co_u32_e32 v115, vcc, 0, v83, vcc
	v_add_co_u32_e32 v116, vcc, s7, v82
	s_mov_b32 s7, 0x18000
	s_nop 0
	v_addc_co_u32_e32 v117, vcc, 0, v83, vcc
	v_add_co_u32_e32 v118, vcc, s7, v82
	s_mov_b32 s7, 0x1e000
	s_nop 0
	v_addc_co_u32_e32 v119, vcc, 0, v83, vcc
	v_add_co_u32_e32 v120, vcc, s7, v82
	s_mov_b32 s7, 0x24000
	s_nop 0
	v_addc_co_u32_e32 v121, vcc, 0, v83, vcc
	v_add_co_u32_e32 v122, vcc, s7, v82
	s_mov_b32 s7, 0x2a000
	s_nop 0
	v_addc_co_u32_e32 v123, vcc, 0, v83, vcc
	v_add_co_u32_e32 v124, vcc, s7, v82
	s_mov_b32 s7, 0x30000
	s_nop 0
	v_addc_co_u32_e32 v125, vcc, 0, v83, vcc
	ds_read_b128 v[18:21], v62
	ds_read_b128 v[14:17], v62 offset:16
	ds_read_b128 v[10:13], v62 offset:32
	ds_read_b128 v[6:9], v62 offset:48
	ds_read_b128 v[2:5], v62 offset:4096
	ds_read_b128 v[22:25], v62 offset:4112
	ds_read_b128 v[38:41], v62 offset:8192
	ds_read_b128 v[34:37], v62 offset:8208
	ds_read_b128 v[30:33], v62 offset:12288
	ds_read_b128 v[26:29], v62 offset:12304
	ds_read_b128 v[46:49], v62 offset:16384
	ds_read_b128 v[42:45], v62 offset:16400
	ds_read_b128 v[50:53], v62 offset:4128
	ds_read_b128 v[54:57], v62 offset:4144
	ds_read_b128 v[90:93], v62 offset:8224
	ds_read_b128 v[94:97], v62 offset:8240
	ds_read_b128 v[98:101], v62 offset:12320
	ds_read_b128 v[58:61], v62 offset:12336
	ds_read_b128 v[102:105], v62 offset:16416
	ds_read_b128 v[106:109], v62 offset:16432
	global_load_dword v110, v[82:83], off
	v_add_co_u32_e32 v126, vcc, s7, v82
	s_mov_b32 s7, 0x36000
	s_nop 0
	v_addc_co_u32_e32 v127, vcc, 0, v83, vcc
	v_add_co_u32_e32 v128, vcc, s7, v82
	s_mov_b32 s7, 0x3c000
	s_nop 0
	v_addc_co_u32_e32 v129, vcc, 0, v83, vcc
	v_add_co_u32_e32 v130, vcc, s7, v82
	s_mov_b32 s7, 0x42000
	s_nop 0
	v_addc_co_u32_e32 v131, vcc, 0, v83, vcc
	v_add_co_u32_e32 v132, vcc, s7, v82
	s_mov_b32 s7, 0x48000
	s_nop 0
	v_addc_co_u32_e32 v133, vcc, 0, v83, vcc
	global_load_dword v112, v[112:113], off
	s_nop 0
	global_load_dword v114, v[114:115], off
	s_nop 0
	global_load_dword v116, v[116:117], off
	s_nop 0
	global_load_dword v118, v[118:119], off
	s_nop 0
	global_load_dword v120, v[120:121], off
	s_nop 0
	global_load_dword v122, v[122:123], off
	s_nop 0
	global_load_dword v124, v[124:125], off
	v_add_co_u32_e32 v134, vcc, s7, v82
	s_mov_b32 s7, 0x4e000
	s_nop 0
	v_addc_co_u32_e32 v135, vcc, 0, v83, vcc
	v_add_co_u32_e32 v136, vcc, s7, v82
	s_mov_b32 s7, 0x54000
	s_nop 0
	v_addc_co_u32_e32 v137, vcc, 0, v83, vcc
	v_add_co_u32_e32 v138, vcc, s7, v82
	s_mov_b32 s7, 0x5a000
	s_nop 0
	v_addc_co_u32_e32 v139, vcc, 0, v83, vcc
	v_add_co_u32_e32 v82, vcc, s7, v82
	s_waitcnt lgkmcnt(14)
	v_mov_b32_e32 v140, v18
	v_addc_co_u32_e32 v83, vcc, 0, v83, vcc
	global_load_dword v126, v[126:127], off
	s_nop 0
	global_load_dword v128, v[128:129], off
	s_nop 0
	global_load_dword v130, v[130:131], off
	s_nop 0
	global_load_dword v132, v[132:133], off
	s_nop 0
	global_load_dword v134, v[134:135], off
	s_nop 0
	global_load_dword v136, v[136:137], off
	s_nop 0
	global_load_dword v138, v[138:139], off
	s_nop 0
	global_load_dword v82, v[82:83], off
	v_mov_b32_e32 v141, v2
	v_mov_b32_e32 v2, v19
	v_mov_b32_e32 v18, v20
	v_mov_b32_e32 v19, v4
	v_mov_b32_e32 v4, v21
	s_waitcnt lgkmcnt(13)
	v_mov_b32_e32 v20, v38
	s_waitcnt lgkmcnt(11)
	v_mov_b32_e32 v21, v30
	v_mov_b32_e32 v30, v39
	v_mov_b32_e32 v38, v40
	v_mov_b32_e32 v39, v32
	v_mov_b32_e32 v32, v41
	v_mov_b32_e32 v40, v14
	v_mov_b32_e32 v41, v22
	v_mov_b32_e32 v22, v15
	v_mov_b32_e32 v14, v16
	v_mov_b32_e32 v15, v24
	v_mov_b32_e32 v24, v17
	v_mov_b32_e32 v16, v34
	s_waitcnt lgkmcnt(10)
	v_mov_b32_e32 v17, v26
	v_mov_b32_e32 v26, v35
	v_mov_b32_e32 v34, v36
	v_mov_b32_e32 v35, v28
	v_mov_b32_e32 v28, v37
	v_mov_b32_e32 v36, v10
	s_waitcnt lgkmcnt(7)
	v_mov_b32_e32 v37, v50
	v_mov_b32_e32 v50, v11
	v_mov_b32_e32 v10, v12
	v_mov_b32_e32 v11, v52
	v_mov_b32_e32 v52, v13
	s_waitcnt lgkmcnt(5)
	v_mov_b32_e32 v12, v90
	s_waitcnt lgkmcnt(3)
	v_mov_b32_e32 v13, v98
	v_mov_b32_e32 v98, v91
	v_mov_b32_e32 v90, v92
	v_mov_b32_e32 v91, v100
	v_mov_b32_e32 v100, v93
	v_mov_b32_e32 v92, v6
	v_mov_b32_e32 v93, v54
	s_waitcnt vmcnt(15)
	v_pk_fma_f32 v[78:79], v[110:111], v[140:141], v[78:79] op_sel_hi:[0,1,1]
	v_pk_fma_f32 v[20:21], v[110:111], v[20:21], v[80:81] op_sel_hi:[0,1,1]
	v_fmac_f32_e32 v71, v110, v46
	v_mov_b32_e32 v54, v7
	v_mov_b32_e32 v6, v8
	v_mov_b32_e32 v7, v56
	v_mov_b32_e32 v56, v9
	v_mov_b32_e32 v8, v94
	s_waitcnt lgkmcnt(2)
	v_mov_b32_e32 v9, v58
	v_mov_b32_e32 v58, v95
	s_add_u32 s8, s8, 0x60000
	v_mov_b32_e32 v94, v96
	v_mov_b32_e32 v95, v60
	s_addc_u32 s9, s9, 0
	v_mov_b32_e32 v60, v97
	s_waitcnt vmcnt(14)
	v_pk_fma_f32 v[2:3], v[112:113], v[2:3], v[78:79] op_sel_hi:[0,1,1]
	v_pk_fma_f32 v[20:21], v[112:113], v[30:31], v[20:21] op_sel_hi:[0,1,1]
	v_fmac_f32_e32 v71, v112, v47
	s_waitcnt vmcnt(13)
	v_pk_fma_f32 v[2:3], v[114:115], v[18:19], v[2:3] op_sel_hi:[0,1,1]
	v_pk_fma_f32 v[18:19], v[114:115], v[38:39], v[20:21] op_sel_hi:[0,1,1]
	v_fmac_f32_e32 v71, v114, v48
	s_waitcnt vmcnt(12)
	v_pk_fma_f32 v[2:3], v[116:117], v[4:5], v[2:3] op_sel_hi:[0,1,1]
	v_pk_fma_f32 v[4:5], v[116:117], v[32:33], v[18:19] op_sel_hi:[0,1,1]
	v_fmac_f32_e32 v71, v116, v49
	s_waitcnt vmcnt(11)
	v_pk_fma_f32 v[2:3], v[118:119], v[40:41], v[2:3] op_sel_hi:[0,1,1]
	v_pk_fma_f32 v[4:5], v[118:119], v[16:17], v[4:5] op_sel_hi:[0,1,1]
	v_fmac_f32_e32 v71, v118, v42
	s_waitcnt vmcnt(10)
	v_pk_fma_f32 v[2:3], v[120:121], v[22:23], v[2:3] op_sel_hi:[0,1,1]
	v_pk_fma_f32 v[4:5], v[120:121], v[26:27], v[4:5] op_sel_hi:[0,1,1]
	v_fmac_f32_e32 v71, v120, v43
	s_waitcnt vmcnt(9)
	v_pk_fma_f32 v[2:3], v[122:123], v[14:15], v[2:3] op_sel_hi:[0,1,1]
	v_pk_fma_f32 v[4:5], v[122:123], v[34:35], v[4:5] op_sel_hi:[0,1,1]
	v_fmac_f32_e32 v71, v122, v44
	s_waitcnt vmcnt(8)
	v_pk_fma_f32 v[2:3], v[124:125], v[24:25], v[2:3] op_sel_hi:[0,1,1]
	v_pk_fma_f32 v[4:5], v[124:125], v[28:29], v[4:5] op_sel_hi:[0,1,1]
	v_fmac_f32_e32 v71, v124, v45
	s_waitcnt vmcnt(7)
	v_pk_fma_f32 v[2:3], v[126:127], v[36:37], v[2:3] op_sel_hi:[0,1,1]
	v_pk_fma_f32 v[4:5], v[126:127], v[12:13], v[4:5] op_sel_hi:[0,1,1]
	s_waitcnt lgkmcnt(1)
	v_fmac_f32_e32 v71, v126, v102
	s_waitcnt vmcnt(6)
	v_pk_fma_f32 v[2:3], v[128:129], v[50:51], v[2:3] op_sel_hi:[0,1,1]
	v_pk_fma_f32 v[4:5], v[128:129], v[98:99], v[4:5] op_sel_hi:[0,1,1]
	v_fmac_f32_e32 v71, v128, v103
	s_waitcnt vmcnt(5)
	v_pk_fma_f32 v[2:3], v[130:131], v[10:11], v[2:3] op_sel_hi:[0,1,1]
	v_pk_fma_f32 v[4:5], v[130:131], v[90:91], v[4:5] op_sel_hi:[0,1,1]
	v_fmac_f32_e32 v71, v130, v104
	s_waitcnt vmcnt(4)
	v_pk_fma_f32 v[2:3], v[132:133], v[52:53], v[2:3] op_sel_hi:[0,1,1]
	v_pk_fma_f32 v[4:5], v[132:133], v[100:101], v[4:5] op_sel_hi:[0,1,1]
	v_fmac_f32_e32 v71, v132, v105
	s_waitcnt vmcnt(3)
	v_pk_fma_f32 v[2:3], v[134:135], v[92:93], v[2:3] op_sel_hi:[0,1,1]
	v_pk_fma_f32 v[4:5], v[134:135], v[8:9], v[4:5] op_sel_hi:[0,1,1]
	s_waitcnt lgkmcnt(0)
	v_fmac_f32_e32 v71, v134, v106
	s_waitcnt vmcnt(2)
	v_pk_fma_f32 v[2:3], v[136:137], v[54:55], v[2:3] op_sel_hi:[0,1,1]
	v_pk_fma_f32 v[4:5], v[136:137], v[58:59], v[4:5] op_sel_hi:[0,1,1]
	v_fmac_f32_e32 v71, v136, v107
	s_waitcnt vmcnt(1)
	v_pk_fma_f32 v[2:3], v[138:139], v[6:7], v[2:3] op_sel_hi:[0,1,1]
	v_pk_fma_f32 v[4:5], v[138:139], v[94:95], v[4:5] op_sel_hi:[0,1,1]
	v_fmac_f32_e32 v71, v138, v108
	v_add_u32_e32 v62, 64, v62
	s_cmp_eq_u32 s8, 0x180000
	s_waitcnt vmcnt(0)
	v_pk_fma_f32 v[78:79], v[82:83], v[56:57], v[2:3] op_sel_hi:[0,1,1]
	v_pk_fma_f32 v[80:81], v[82:83], v[60:61], v[4:5] op_sel_hi:[0,1,1]
	v_fmac_f32_e32 v71, v82, v109
	s_cbranch_scc0 .LBB0_105
	s_movk_i32 s7, 0x280
	v_mul_lo_u32 v2, v72, s7
	v_lshlrev_b32_e32 v62, 2, v74
	v_add3_u32 v2, 0, v2, v62
	s_movk_i32 s7, 0xa0
	v_add_u32_e32 v3, 0x5000, v2
	v_cmp_gt_i32_e32 vcc, s7, v70
	ds_write2_b32 v3, v78, v79 offset1:32
	ds_write2_b32 v3, v80, v81 offset0:64 offset1:96
	ds_write_b32 v2, v71 offset:20992
	s_waitcnt lgkmcnt(0)
	s_barrier
	s_and_saveexec_b64 s[8:9], vcc
	s_cbranch_execz .LBB0_62
	s_load_dwordx16 s[72:87], s[0:1], 0x0
	s_mul_i32 s7, s6, 0x1800
	s_add_i32 s7, s7, s4
	v_or_b32_e32 v2, s7, v74
	v_ashrrev_i32_e32 v3, 31, v2
	s_waitcnt lgkmcnt(0)
	v_lshl_add_u64 v[2:3], v[2:3], 2, s[82:83]
	global_load_dword v22, v[2:3], off
	v_lshlrev_b32_e32 v4, 7, v72
	v_ashrrev_i32_e32 v73, 31, v72
	v_add3_u32 v6, 0, v62, v4
	v_mov_b64_e32 v[2:3], s[44:45]
	v_mad_i64_i32 v[4:5], s[6:7], s6, 5, v[72:73]
	v_add_u32_e32 v7, 0x5000, v6
	v_add_u32_e32 v8, 0x5400, v6
	v_add_u32_e32 v10, 0x5a00, v6
	v_add_u32_e32 v12, 0x5e00, v6
	v_add_u32_e32 v14, 0x6400, v6
	v_add_u32_e32 v16, 0x6800, v6
	v_add_u32_e32 v18, 0x6e00, v6
	v_add_u32_e32 v20, 0x7200, v6
	v_mad_u64_u32 v[2:3], s[6:7], v4, s63, v[2:3]
	ds_read2_b32 v[6:7], v7 offset1:160
	ds_read2_b32 v[8:9], v8 offset0:64 offset1:224
	ds_read2_b32 v[10:11], v10 offset1:160
	ds_read2_b32 v[12:13], v12 offset0:64 offset1:224
	ds_read2_b32 v[14:15], v14 offset1:160
	ds_read2_b32 v[16:17], v16 offset0:64 offset1:224
	ds_read2_b32 v[18:19], v18 offset1:160
	ds_read2_b32 v[20:21], v20 offset0:64 offset1:224
	s_waitcnt lgkmcnt(7)
	v_add_f32_e32 v4, 0, v6
	v_add_f32_e32 v4, v4, v7
	s_waitcnt lgkmcnt(6)
	v_add_f32_e32 v4, v4, v8
	v_add_f32_e32 v4, v4, v9
	s_waitcnt lgkmcnt(5)
	v_add_f32_e32 v4, v4, v10
	v_add_f32_e32 v4, v4, v11
	s_waitcnt lgkmcnt(4)
	v_add_f32_e32 v4, v4, v12
	v_add_f32_e32 v4, v4, v13
	s_waitcnt lgkmcnt(3)
	v_add_f32_e32 v4, v4, v14
	v_add_f32_e32 v4, v4, v15
	s_waitcnt lgkmcnt(2)
	v_add_f32_e32 v4, v4, v16
	v_add_f32_e32 v4, v4, v17
	s_waitcnt lgkmcnt(1)
	v_add_f32_e32 v4, v4, v18
	v_add_f32_e32 v4, v4, v19
	v_mad_i32_i24 v3, v5, s63, v3
	s_waitcnt lgkmcnt(0)
	v_add_f32_e32 v4, v4, v20
	v_lshl_add_u64 v[2:3], s[4:5], 2, v[2:3]
	v_add_f32_e32 v4, v4, v21
	v_lshl_add_u64 v[2:3], v[2:3], 0, v[62:63]
	s_waitcnt vmcnt(0)
	v_add_f32_e32 v4, v4, v22
	global_store_dword v[2:3], v4, off sc1
	s_branch .LBB0_62

.LBB0_132:
	s_barrier
	s_waitcnt vmcnt(7)
	ds_write2_b32 v74, v2, v3 offset1:1
	ds_write2_b32 v74, v4, v5 offset0:2 offset1:3
	s_waitcnt vmcnt(6)
	ds_write2_b32 v74, v6, v7 offset0:4 offset1:5
	ds_write2_b32 v74, v8, v9 offset0:6 offset1:7
	v_add_u32_e32 v2, 0x4100, v74
	s_waitcnt vmcnt(5)
	ds_write2_b32 v2, v10, v11 offset1:1
	v_add_u32_e32 v2, 0x4108, v74
	ds_write2_b32 v2, v12, v13 offset1:1
	v_add_u32_e32 v2, 0x4110, v74
	s_waitcnt vmcnt(4)
	ds_write2_b32 v2, v14, v15 offset1:1
	v_add_u32_e32 v2, 0x4118, v74
	ds_write2_b32 v2, v16, v17 offset1:1
	v_add_u32_e32 v2, 0x8200, v74
	s_waitcnt vmcnt(3)
	ds_write2_b32 v2, v18, v19 offset1:1
	v_add_u32_e32 v2, 0x8208, v74
	ds_write2_b32 v2, v20, v21 offset1:1
	v_add_u32_e32 v2, 0x8210, v74
	s_waitcnt vmcnt(2)
	ds_write2_b32 v2, v22, v23 offset1:1
	v_add_u32_e32 v2, 0x8218, v74
	ds_write2_b32 v2, v24, v25 offset1:1
	v_add_u32_e32 v2, 0xc300, v74
	s_waitcnt vmcnt(1)
	ds_write2_b32 v2, v26, v27 offset1:1
	v_add_u32_e32 v2, 0xc308, v74
	ds_write2_b32 v2, v28, v29 offset1:1
	v_add_u32_e32 v2, 0xc310, v74
	s_waitcnt vmcnt(0)
	ds_write2_b32 v2, v30, v31 offset1:1
	v_add_u32_e32 v2, 0xc318, v74
	ds_write2_b32 v2, v32, v33 offset1:1
	s_waitcnt lgkmcnt(0)
	s_barrier
	ds_read2_b32 v[2:3], v75 offset1:65
	ds_read2_b32 v[4:5], v75 offset0:130 offset1:195
	v_add_u32_e32 v8, 0x400, v75
	ds_read2_b32 v[6:7], v8 offset0:4 offset1:69
	ds_read2_b32 v[8:9], v8 offset0:134 offset1:199
	v_add_u32_e32 v10, 0x4400, v75
	s_waitcnt lgkmcnt(3)
	v_cvt_pk_bf16_f32 v2, v2, v3
	s_waitcnt lgkmcnt(2)
	v_cvt_pk_bf16_f32 v3, v4, v5
	s_waitcnt lgkmcnt(1)
	v_cvt_pk_bf16_f32 v4, v6, v7
	v_add_u32_e32 v6, 0x4000, v75
	v_add_u32_e32 v12, 0x4600, v75
	s_waitcnt lgkmcnt(0)
	v_cvt_pk_bf16_f32 v5, v8, v9
	ds_read2_b32 v[6:7], v6 offset0:64 offset1:129
	v_add_u32_e32 v8, 0x4200, v75
	ds_read2_b32 v[10:11], v10 offset0:68 offset1:133
	ds_read2_b32 v[12:13], v12 offset0:70 offset1:135
	ds_read2_b32 v[8:9], v8 offset0:66 offset1:131
	global_store_dwordx4 v[70:71], v[2:5], off sc1
	s_andn2_b64 vcc, exec, s[14:15]
	v_mov_b32_e32 v14, v42
	s_waitcnt lgkmcnt(3)
	v_cvt_pk_bf16_f32 v2, v6, v7
	s_waitcnt lgkmcnt(2)
	v_cvt_pk_bf16_f32 v4, v10, v11
	s_waitcnt lgkmcnt(1)
	v_cvt_pk_bf16_f32 v5, v12, v13
	v_add_u32_e32 v6, 0x8000, v75
	v_add_u32_e32 v10, 0x8400, v75
	v_add_u32_e32 v12, 0x8800, v75
	s_waitcnt lgkmcnt(0)
	v_cvt_pk_bf16_f32 v3, v8, v9
	ds_read2_b32 v[6:7], v6 offset0:128 offset1:193
	ds_read2_b32 v[8:9], v10 offset0:2 offset1:67
	ds_read2_b32 v[10:11], v10 offset0:132 offset1:197
	ds_read2_b32 v[12:13], v12 offset0:6 offset1:71
	global_store_dwordx4 v[70:71], v[2:5], off offset:128 sc1
	v_mov_b32_e32 v15, v43
	v_mov_b32_e32 v16, v44
	s_waitcnt lgkmcnt(3)
	v_cvt_pk_bf16_f32 v2, v6, v7
	s_waitcnt lgkmcnt(2)
	v_cvt_pk_bf16_f32 v3, v8, v9
	s_waitcnt lgkmcnt(1)
	v_cvt_pk_bf16_f32 v4, v10, v11
	s_waitcnt lgkmcnt(0)
	v_cvt_pk_bf16_f32 v5, v12, v13
	v_add_u32_e32 v6, 0xc200, v75
	v_add_u32_e32 v8, 0xc400, v75
	v_add_u32_e32 v10, 0xc600, v75
	v_add_u32_e32 v12, 0xc800, v75
	ds_read2_b32 v[6:7], v6 offset0:64 offset1:129
	ds_read2_b32 v[8:9], v8 offset0:66 offset1:131
	ds_read2_b32 v[10:11], v10 offset0:68 offset1:133
	ds_read2_b32 v[12:13], v12 offset0:70 offset1:135
	global_store_dwordx4 v[70:71], v[2:5], off offset:256 sc1
	v_mov_b32_e32 v17, v45
	v_mov_b32_e32 v18, v54
	s_waitcnt lgkmcnt(3)
	v_cvt_pk_bf16_f32 v2, v6, v7
	s_waitcnt lgkmcnt(2)
	v_cvt_pk_bf16_f32 v3, v8, v9
	s_waitcnt lgkmcnt(1)
	v_cvt_pk_bf16_f32 v4, v10, v11
	s_waitcnt lgkmcnt(0)
	v_cvt_pk_bf16_f32 v5, v12, v13
	global_store_dwordx4 v[70:71], v[2:5], off offset:384 sc1
	v_mov_b64_e32 v[70:71], v[72:73]
	v_mov_b32_e32 v6, v34
	v_mov_b32_e32 v2, v38
	v_mov_b32_e32 v3, v39
	v_mov_b32_e32 v4, v40
	v_mov_b32_e32 v5, v41
	v_mov_b32_e32 v7, v35
	v_mov_b32_e32 v8, v36
	v_mov_b32_e32 v9, v37
	v_mov_b32_e32 v10, v46
	v_mov_b32_e32 v11, v47
	v_mov_b32_e32 v12, v48
	v_mov_b32_e32 v13, v49
	v_mov_b32_e32 v19, v55
	v_mov_b32_e32 v20, v56
	v_mov_b32_e32 v21, v57
	v_mov_b32_e32 v22, v50
	v_mov_b32_e32 v23, v51
	v_mov_b32_e32 v24, v52
	v_mov_b32_e32 v25, v53
	v_mov_b32_e32 v26, v62
	v_mov_b32_e32 v27, v63
	v_mov_b32_e32 v28, v64
	v_mov_b32_e32 v29, v65
	v_mov_b32_e32 v30, v58
	v_mov_b32_e32 v31, v59
	v_mov_b32_e32 v32, v60
	v_mov_b32_e32 v33, v61
	s_cbranch_vccz .LBB0_147

.LBB0_705:
	s_barrier
	s_waitcnt vmcnt(7)
	ds_write2_b32 v74, v2, v3 offset1:1
	ds_write2_b32 v74, v4, v5 offset0:2 offset1:3
	s_waitcnt vmcnt(6)
	ds_write2_b32 v74, v6, v7 offset0:4 offset1:5
	ds_write2_b32 v74, v8, v9 offset0:6 offset1:7
	v_add_u32_e32 v2, 0x4100, v74
	s_waitcnt vmcnt(5)
	ds_write2_b32 v2, v10, v11 offset1:1
	v_add_u32_e32 v2, 0x4108, v74
	ds_write2_b32 v2, v12, v13 offset1:1
	v_add_u32_e32 v2, 0x4110, v74
	s_waitcnt vmcnt(4)
	ds_write2_b32 v2, v14, v15 offset1:1
	v_add_u32_e32 v2, 0x4118, v74
	ds_write2_b32 v2, v16, v17 offset1:1
	v_add_u32_e32 v2, 0x8200, v74
	s_waitcnt vmcnt(3)
	ds_write2_b32 v2, v18, v19 offset1:1
	v_add_u32_e32 v2, 0x8208, v74
	ds_write2_b32 v2, v20, v21 offset1:1
	v_add_u32_e32 v2, 0x8210, v74
	s_waitcnt vmcnt(2)
	ds_write2_b32 v2, v22, v23 offset1:1
	v_add_u32_e32 v2, 0x8218, v74
	ds_write2_b32 v2, v24, v25 offset1:1
	v_add_u32_e32 v2, 0xc300, v74
	s_waitcnt vmcnt(1)
	ds_write2_b32 v2, v26, v27 offset1:1
	v_add_u32_e32 v2, 0xc308, v74
	ds_write2_b32 v2, v28, v29 offset1:1
	v_add_u32_e32 v2, 0xc310, v74
	s_waitcnt vmcnt(0)
	ds_write2_b32 v2, v30, v31 offset1:1
	v_add_u32_e32 v2, 0xc318, v74
	ds_write2_b32 v2, v32, v33 offset1:1
	s_waitcnt lgkmcnt(0)
	s_barrier
	ds_read2_b32 v[2:3], v75 offset1:65
	ds_read2_b32 v[4:5], v75 offset0:130 offset1:195
	v_add_u32_e32 v8, 0x400, v75
	ds_read2_b32 v[6:7], v8 offset0:4 offset1:69
	ds_read2_b32 v[8:9], v8 offset0:134 offset1:199
	v_add_u32_e32 v10, 0x4400, v75
	s_waitcnt lgkmcnt(3)
	v_cvt_pk_bf16_f32 v2, v2, v3
	s_waitcnt lgkmcnt(2)
	v_cvt_pk_bf16_f32 v3, v4, v5
	s_waitcnt lgkmcnt(1)
	v_cvt_pk_bf16_f32 v4, v6, v7
	v_add_u32_e32 v6, 0x4000, v75
	v_add_u32_e32 v12, 0x4600, v75
	s_waitcnt lgkmcnt(0)
	v_cvt_pk_bf16_f32 v5, v8, v9
	ds_read2_b32 v[6:7], v6 offset0:64 offset1:129
	v_add_u32_e32 v8, 0x4200, v75
	ds_read2_b32 v[10:11], v10 offset0:68 offset1:133
	ds_read2_b32 v[12:13], v12 offset0:70 offset1:135
	ds_read2_b32 v[8:9], v8 offset0:66 offset1:131
	global_store_dwordx4 v[70:71], v[2:5], off sc1
	s_cmpk_lt_i32 s25, 0x13d0
	s_mov_b32 s12, s25
	s_waitcnt lgkmcnt(3)
	v_cvt_pk_bf16_f32 v2, v6, v7
	s_waitcnt lgkmcnt(2)
	v_cvt_pk_bf16_f32 v4, v10, v11
	s_waitcnt lgkmcnt(1)
	v_cvt_pk_bf16_f32 v5, v12, v13
	v_add_u32_e32 v6, 0x8000, v75
	v_add_u32_e32 v10, 0x8400, v75
	v_add_u32_e32 v12, 0x8800, v75
	s_waitcnt lgkmcnt(0)
	v_cvt_pk_bf16_f32 v3, v8, v9
	ds_read2_b32 v[6:7], v6 offset0:128 offset1:193
	ds_read2_b32 v[8:9], v10 offset0:2 offset1:67
	ds_read2_b32 v[10:11], v10 offset0:132 offset1:197
	ds_read2_b32 v[12:13], v12 offset0:6 offset1:71
	global_store_dwordx4 v[70:71], v[2:5], off offset:128 sc1
	v_mov_b32_e32 v14, v42
	v_mov_b32_e32 v15, v43
	s_waitcnt lgkmcnt(3)
	v_cvt_pk_bf16_f32 v2, v6, v7
	s_waitcnt lgkmcnt(2)
	v_cvt_pk_bf16_f32 v3, v8, v9
	s_waitcnt lgkmcnt(1)
	v_cvt_pk_bf16_f32 v4, v10, v11
	s_waitcnt lgkmcnt(0)
	v_cvt_pk_bf16_f32 v5, v12, v13
	v_add_u32_e32 v6, 0xc200, v75
	v_add_u32_e32 v8, 0xc400, v75
	v_add_u32_e32 v10, 0xc600, v75
	v_add_u32_e32 v12, 0xc800, v75
	ds_read2_b32 v[6:7], v6 offset0:64 offset1:129
	ds_read2_b32 v[8:9], v8 offset0:66 offset1:131
	ds_read2_b32 v[10:11], v10 offset0:68 offset1:133
	ds_read2_b32 v[12:13], v12 offset0:70 offset1:135
	global_store_dwordx4 v[70:71], v[2:5], off offset:256 sc1
	v_mov_b32_e32 v16, v44
	v_mov_b32_e32 v17, v45
	s_waitcnt lgkmcnt(3)
	v_cvt_pk_bf16_f32 v2, v6, v7
	s_waitcnt lgkmcnt(2)
	v_cvt_pk_bf16_f32 v3, v8, v9
	s_waitcnt lgkmcnt(1)
	v_cvt_pk_bf16_f32 v4, v10, v11
	s_waitcnt lgkmcnt(0)
	v_cvt_pk_bf16_f32 v5, v12, v13
	global_store_dwordx4 v[70:71], v[2:5], off offset:384 sc1
	v_mov_b64_e32 v[70:71], v[72:73]
	v_mov_b32_e32 v6, v34
	v_mov_b32_e32 v2, v38
	v_mov_b32_e32 v3, v39
	v_mov_b32_e32 v4, v40
	v_mov_b32_e32 v5, v41
	v_mov_b32_e32 v7, v35
	v_mov_b32_e32 v8, v36
	v_mov_b32_e32 v9, v37
	v_mov_b32_e32 v10, v46
	v_mov_b32_e32 v11, v47
	v_mov_b32_e32 v12, v48
	v_mov_b32_e32 v13, v49
	v_mov_b32_e32 v18, v54
	v_mov_b32_e32 v19, v55
	v_mov_b32_e32 v20, v56
	v_mov_b32_e32 v21, v57
	v_mov_b32_e32 v22, v50
	v_mov_b32_e32 v23, v51
	v_mov_b32_e32 v24, v52
	v_mov_b32_e32 v25, v53
	v_mov_b32_e32 v26, v62
	v_mov_b32_e32 v27, v63
	v_mov_b32_e32 v28, v64
	v_mov_b32_e32 v29, v65
	v_mov_b32_e32 v30, v58
	v_mov_b32_e32 v31, v59
	v_mov_b32_e32 v32, v60
	v_mov_b32_e32 v33, v61
	s_cbranch_scc0 .LBB0_728

.LBB0_1102:
	s_or_b64 exec, exec, s[14:15]
	v_lshlrev_b32_e32 v22, 2, v10
	global_load_dwordx4 v[30:33], v22, s[6:7]
	global_load_dwordx4 v[10:13], v22, s[6:7] offset:16
	v_readlane_b32 s56, v197, 18
	v_readlane_b32 s60, v197, 22
	v_readlane_b32 s61, v197, 23
	s_nop 4
	global_load_dwordx4 v[38:41], v22, s[60:61]
	global_load_dwordx4 v[26:29], v22, s[60:61] offset:16
	global_load_dwordx4 v[34:37], v22, s[8:9]
	s_nop 0
	global_load_dwordx4 v[22:25], v22, s[8:9] offset:16
	s_waitcnt vmcnt(0)
	v_lshlrev_b32_e32 v120, 16, v90
	v_and_b32_e32 v121, 0xffff0000, v90
	v_lshlrev_b32_e32 v90, 16, v91
	v_and_b32_e32 v91, 0xffff0000, v91
	v_lshlrev_b32_e32 v128, 16, v92
	v_and_b32_e32 v129, 0xffff0000, v92
	v_lshlrev_b32_e32 v92, 16, v93
	v_and_b32_e32 v93, 0xffff0000, v93
	v_readlane_b32 s57, v197, 19
	v_readlane_b32 s58, v197, 20
	v_readlane_b32 s59, v197, 21
	v_readlane_b32 s62, v197, 24
	v_readlane_b32 s63, v197, 25
	v_readlane_b32 s64, v197, 26
	v_readlane_b32 s65, v197, 27
	v_readlane_b32 s66, v197, 28
	v_readlane_b32 s67, v197, 29
	v_readlane_b32 s68, v197, 30
	v_readlane_b32 s69, v197, 31
	v_readlane_b32 s70, v197, 32
	v_readlane_b32 s71, v197, 33
	v_lshlrev_b32_e32 v118, 16, v82
	v_and_b32_e32 v119, 0xffff0000, v82
	v_lshlrev_b32_e32 v82, 16, v83
	v_and_b32_e32 v83, 0xffff0000, v83
	v_lshlrev_b32_e32 v126, 16, v84
	v_and_b32_e32 v127, 0xffff0000, v84
	v_lshlrev_b32_e32 v84, 16, v85
	v_and_b32_e32 v85, 0xffff0000, v85
	v_lshlrev_b32_e32 v122, 16, v86
	v_and_b32_e32 v123, 0xffff0000, v86
	v_lshlrev_b32_e32 v86, 16, v87
	v_and_b32_e32 v87, 0xffff0000, v87
	v_lshlrev_b32_e32 v130, 16, v88
	v_and_b32_e32 v131, 0xffff0000, v88
	v_lshlrev_b32_e32 v88, 16, v89
	v_and_b32_e32 v89, 0xffff0000, v89
	v_readlane_b32 s56, v196, 6
	v_lshlrev_b32_e32 v116, 16, v94
	v_and_b32_e32 v117, 0xffff0000, v94
	v_lshlrev_b32_e32 v94, 16, v95
	v_and_b32_e32 v95, 0xffff0000, v95
	v_lshlrev_b32_e32 v124, 16, v96
	v_and_b32_e32 v125, 0xffff0000, v96
	v_lshlrev_b32_e32 v96, 16, v97
	v_and_b32_e32 v97, 0xffff0000, v97
	v_mov_b32_e32 v115, v101
	v_readlane_b32 s68, v196, 18
	v_readlane_b32 s69, v196, 19
	v_lshlrev_b32_e32 v138, 16, v80
	v_and_b32_e32 v139, 0xffff0000, v80
	v_lshl_add_u64 v[114:115], s[68:69], 0, v[114:115]
	v_lshl_add_u64 v[114:115], v[114:115], 0, v[100:101]
	v_lshlrev_b32_e32 v136, 16, v76
	v_and_b32_e32 v137, 0xffff0000, v76
	v_lshlrev_b32_e32 v134, 16, v78
	v_and_b32_e32 v135, 0xffff0000, v78
	v_lshlrev_b32_e32 v78, 16, v79
	v_and_b32_e32 v79, 0xffff0000, v79
	v_lshlrev_b32_e32 v80, 16, v81
	v_and_b32_e32 v81, 0xffff0000, v81
	v_lshlrev_b32_e32 v132, 16, v74
	v_and_b32_e32 v133, 0xffff0000, v74
	v_lshlrev_b32_e32 v74, 16, v75
	v_and_b32_e32 v75, 0xffff0000, v75
	v_lshl_add_u64 v[98:99], v[98:99], 0, s[2:3]
	v_cmp_lt_u64_e32 vcc, s[12:13], v[98:99]
	s_or_b64 s[10:11], vcc, s[10:11]
	v_add_u32_e32 v1, s16, v1
	v_readlane_b32 s57, v196, 7
	v_readlane_b32 s58, v196, 8
	v_readlane_b32 s59, v196, 9
	v_readlane_b32 s60, v196, 10
	v_readlane_b32 s61, v196, 11
	v_pk_mul_f32 v[140:141], v[30:31], v[120:121]
	v_pk_mul_f32 v[142:143], v[32:33], v[90:91]
	v_pk_mul_f32 v[144:145], v[10:11], v[128:129]
	v_pk_mul_f32 v[146:147], v[12:13], v[92:93]
	v_pk_fma_f32 v[118:119], v[38:39], v[118:119], v[140:141]
	v_pk_fma_f32 v[82:83], v[40:41], v[82:83], v[142:143]
	v_pk_fma_f32 v[126:127], v[26:27], v[126:127], v[144:145]
	v_pk_fma_f32 v[84:85], v[28:29], v[84:85], v[146:147]
	v_pk_fma_f32 v[118:119], v[34:35], v[122:123], v[118:119]
	v_pk_fma_f32 v[82:83], v[36:37], v[86:87], v[82:83]
	v_pk_fma_f32 v[126:127], v[22:23], v[130:131], v[126:127]
	v_pk_fma_f32 v[84:85], v[24:25], v[88:89], v[84:85]
	v_pk_mul_f32 v[152:153], v[10:11], v[130:131]
	v_pk_mul_f32 v[116:117], v[118:119], v[116:117]
	v_pk_mul_f32 v[94:95], v[82:83], v[94:95]
	v_pk_mul_f32 v[118:119], v[126:127], v[124:125]
	v_pk_mul_f32 v[96:97], v[84:85], v[96:97]
	v_pk_fma_f32 v[128:129], v[26:27], v[128:129], v[152:153]
	v_cvt_pk_bf16_f32 v82, v116, v117
	v_cvt_pk_bf16_f32 v83, v94, v95
	v_cvt_pk_bf16_f32 v84, v118, v119
	v_cvt_pk_bf16_f32 v85, v96, v97
	v_pk_mul_f32 v[148:149], v[30:31], v[122:123]
	v_pk_mul_f32 v[150:151], v[32:33], v[86:87]
	global_store_dwordx4 v[114:115], v[82:85], off sc1
	v_pk_fma_f32 v[120:121], v[38:39], v[120:121], v[148:149]
	v_pk_fma_f32 v[90:91], v[40:41], v[90:91], v[150:151]
	v_pk_fma_f32 v[82:83], v[22:23], v[138:139], v[128:129]
	v_pk_mul_f32 v[84:85], v[12:13], v[88:89]
	v_pk_mul_f32 v[82:83], v[82:83], v[136:137]
	v_pk_fma_f32 v[84:85], v[28:29], v[92:93], v[84:85]
	v_pk_fma_f32 v[120:121], v[34:35], v[134:135], v[120:121]
	v_pk_fma_f32 v[90:91], v[36:37], v[78:79], v[90:91]
	v_cvt_pk_bf16_f32 v76, v82, v83
	v_lshlrev_b32_e32 v82, 16, v77
	v_and_b32_e32 v83, 0xffff0000, v77
	v_pk_fma_f32 v[84:85], v[24:25], v[80:81], v[84:85]
	v_pk_mul_f32 v[120:121], v[120:121], v[132:133]
	v_pk_mul_f32 v[90:91], v[90:91], v[74:75]
	v_pk_mul_f32 v[82:83], v[84:85], v[82:83]
	v_cvt_pk_bf16_f32 v74, v120, v121
	v_cvt_pk_bf16_f32 v75, v90, v91
	v_cvt_pk_bf16_f32 v77, v82, v83
	global_store_dwordx4 v[114:115], v[74:77], off offset:2048 sc1
	v_lshlrev_b32_e32 v82, 16, v70
	v_and_b32_e32 v83, 0xffff0000, v70
	v_pk_mul_f32 v[76:77], v[30:31], v[134:135]
	v_lshlrev_b32_e32 v74, 16, v66
	v_pk_fma_f32 v[76:77], v[38:39], v[122:123], v[76:77]
	v_and_b32_e32 v75, 0xffff0000, v66
	v_pk_fma_f32 v[76:77], v[34:35], v[82:83], v[76:77]
	v_lshlrev_b32_e32 v70, 16, v71
	v_pk_mul_f32 v[74:75], v[76:77], v[74:75]
	v_pk_mul_f32 v[76:77], v[32:33], v[78:79]
	v_and_b32_e32 v71, 0xffff0000, v71
	v_pk_fma_f32 v[76:77], v[40:41], v[86:87], v[76:77]
	v_cvt_pk_bf16_f32 v66, v74, v75
	v_lshlrev_b32_e32 v74, 16, v67
	v_and_b32_e32 v75, 0xffff0000, v67
	v_pk_fma_f32 v[76:77], v[36:37], v[70:71], v[76:77]
	v_lshlrev_b32_e32 v84, 16, v72
	v_pk_mul_f32 v[74:75], v[76:77], v[74:75]
	v_pk_mul_f32 v[76:77], v[10:11], v[138:139]
	v_and_b32_e32 v85, 0xffff0000, v72
	v_pk_fma_f32 v[76:77], v[26:27], v[130:131], v[76:77]
	v_cvt_pk_bf16_f32 v67, v74, v75
	v_lshlrev_b32_e32 v74, 16, v68
	v_and_b32_e32 v75, 0xffff0000, v68
	v_pk_fma_f32 v[76:77], v[22:23], v[84:85], v[76:77]
	v_lshlrev_b32_e32 v72, 16, v73
	v_pk_mul_f32 v[74:75], v[76:77], v[74:75]
	v_pk_mul_f32 v[76:77], v[12:13], v[80:81]
	v_and_b32_e32 v73, 0xffff0000, v73
	v_pk_fma_f32 v[76:77], v[28:29], v[88:89], v[76:77]
	v_cvt_pk_bf16_f32 v68, v74, v75
	v_lshlrev_b32_e32 v74, 16, v69
	v_and_b32_e32 v75, 0xffff0000, v69
	v_pk_fma_f32 v[76:77], v[24:25], v[72:73], v[76:77]
	v_readlane_b32 s62, v196, 12
	v_pk_mul_f32 v[74:75], v[76:77], v[74:75]
	v_lshlrev_b32_e32 v76, 16, v64
	v_cvt_pk_bf16_f32 v69, v74, v75
	v_lshl_add_u64 v[74:75], s[68:69], 0, v[112:113]
	v_lshl_add_u64 v[74:75], v[74:75], 0, v[100:101]
	global_store_dwordx4 v[74:75], v[66:69], off sc1
	v_lshlrev_b32_e32 v74, 16, v62
	v_and_b32_e32 v75, 0xffff0000, v62
	v_pk_mul_f32 v[68:69], v[30:31], v[82:83]
	v_lshlrev_b32_e32 v66, 16, v58
	v_pk_fma_f32 v[68:69], v[38:39], v[134:135], v[68:69]
	v_and_b32_e32 v67, 0xffff0000, v58
	v_pk_fma_f32 v[68:69], v[34:35], v[74:75], v[68:69]
	v_lshlrev_b32_e32 v62, 16, v63
	v_pk_mul_f32 v[66:67], v[68:69], v[66:67]
	v_pk_mul_f32 v[68:69], v[32:33], v[70:71]
	v_and_b32_e32 v63, 0xffff0000, v63
	v_pk_fma_f32 v[68:69], v[40:41], v[78:79], v[68:69]
	v_cvt_pk_bf16_f32 v58, v66, v67
	v_lshlrev_b32_e32 v66, 16, v59
	v_and_b32_e32 v67, 0xffff0000, v59
	v_pk_fma_f32 v[68:69], v[36:37], v[62:63], v[68:69]
	v_and_b32_e32 v77, 0xffff0000, v64
	v_pk_mul_f32 v[66:67], v[68:69], v[66:67]
	v_pk_mul_f32 v[68:69], v[10:11], v[84:85]
	v_cvt_pk_bf16_f32 v59, v66, v67
	v_pk_fma_f32 v[68:69], v[26:27], v[138:139], v[68:69]
	v_lshlrev_b32_e32 v66, 16, v60
	v_and_b32_e32 v67, 0xffff0000, v60
	v_pk_fma_f32 v[68:69], v[22:23], v[76:77], v[68:69]
	v_lshlrev_b32_e32 v64, 16, v65
	v_pk_mul_f32 v[66:67], v[68:69], v[66:67]
	v_pk_mul_f32 v[68:69], v[12:13], v[72:73]
	v_and_b32_e32 v65, 0xffff0000, v65
	v_pk_fma_f32 v[68:69], v[28:29], v[80:81], v[68:69]
	v_cvt_pk_bf16_f32 v60, v66, v67
	v_lshlrev_b32_e32 v66, 16, v61
	v_and_b32_e32 v67, 0xffff0000, v61
	v_pk_fma_f32 v[68:69], v[24:25], v[64:65], v[68:69]
	v_readlane_b32 s63, v196, 13
	v_pk_mul_f32 v[66:67], v[68:69], v[66:67]
	v_lshlrev_b32_e32 v68, 16, v56
	v_cvt_pk_bf16_f32 v61, v66, v67
	v_lshl_add_u64 v[66:67], s[68:69], 0, v[110:111]
	v_lshl_add_u64 v[66:67], v[66:67], 0, v[100:101]
	global_store_dwordx4 v[66:67], v[58:61], off sc1
	v_lshlrev_b32_e32 v66, 16, v54
	v_and_b32_e32 v67, 0xffff0000, v54
	v_pk_mul_f32 v[60:61], v[30:31], v[74:75]
	v_lshlrev_b32_e32 v58, 16, v50
	v_pk_fma_f32 v[60:61], v[38:39], v[82:83], v[60:61]
	v_and_b32_e32 v59, 0xffff0000, v50
	v_pk_fma_f32 v[60:61], v[34:35], v[66:67], v[60:61]
	v_lshlrev_b32_e32 v54, 16, v55
	v_pk_mul_f32 v[58:59], v[60:61], v[58:59]
	v_pk_mul_f32 v[60:61], v[32:33], v[62:63]
	v_and_b32_e32 v55, 0xffff0000, v55
	v_pk_fma_f32 v[60:61], v[40:41], v[70:71], v[60:61]
	v_cvt_pk_bf16_f32 v50, v58, v59
	v_lshlrev_b32_e32 v58, 16, v51
	v_and_b32_e32 v59, 0xffff0000, v51
	v_pk_fma_f32 v[60:61], v[36:37], v[54:55], v[60:61]
	v_and_b32_e32 v69, 0xffff0000, v56
	v_pk_mul_f32 v[58:59], v[60:61], v[58:59]
	v_pk_mul_f32 v[60:61], v[10:11], v[76:77]
	v_cvt_pk_bf16_f32 v51, v58, v59
	v_pk_fma_f32 v[60:61], v[26:27], v[84:85], v[60:61]
	v_lshlrev_b32_e32 v58, 16, v52
	v_and_b32_e32 v59, 0xffff0000, v52
	v_pk_fma_f32 v[60:61], v[22:23], v[68:69], v[60:61]
	v_lshlrev_b32_e32 v56, 16, v57
	v_pk_mul_f32 v[58:59], v[60:61], v[58:59]
	v_pk_mul_f32 v[60:61], v[12:13], v[64:65]
	v_and_b32_e32 v57, 0xffff0000, v57
	v_pk_fma_f32 v[60:61], v[28:29], v[72:73], v[60:61]
	v_cvt_pk_bf16_f32 v52, v58, v59
	v_lshlrev_b32_e32 v58, 16, v53
	v_and_b32_e32 v59, 0xffff0000, v53
	v_pk_fma_f32 v[60:61], v[24:25], v[56:57], v[60:61]
	v_readlane_b32 s64, v196, 14
	v_pk_mul_f32 v[58:59], v[60:61], v[58:59]
	v_lshlrev_b32_e32 v60, 16, v48
	v_cvt_pk_bf16_f32 v53, v58, v59
	v_lshl_add_u64 v[58:59], s[68:69], 0, v[108:109]
	v_lshl_add_u64 v[58:59], v[58:59], 0, v[100:101]
	global_store_dwordx4 v[58:59], v[50:53], off sc1
	v_lshlrev_b32_e32 v58, 16, v46
	v_and_b32_e32 v59, 0xffff0000, v46
	v_pk_mul_f32 v[52:53], v[30:31], v[66:67]
	v_lshlrev_b32_e32 v50, 16, v42
	v_pk_fma_f32 v[52:53], v[38:39], v[74:75], v[52:53]
	v_and_b32_e32 v51, 0xffff0000, v42
	v_pk_fma_f32 v[52:53], v[34:35], v[58:59], v[52:53]
	v_lshlrev_b32_e32 v46, 16, v47
	v_pk_mul_f32 v[50:51], v[52:53], v[50:51]
	v_pk_mul_f32 v[52:53], v[32:33], v[54:55]
	v_and_b32_e32 v47, 0xffff0000, v47
	v_pk_fma_f32 v[52:53], v[40:41], v[62:63], v[52:53]
	v_cvt_pk_bf16_f32 v42, v50, v51
	v_lshlrev_b32_e32 v50, 16, v43
	v_and_b32_e32 v51, 0xffff0000, v43
	v_pk_fma_f32 v[52:53], v[36:37], v[46:47], v[52:53]
	v_and_b32_e32 v61, 0xffff0000, v48
	v_pk_mul_f32 v[50:51], v[52:53], v[50:51]
	v_pk_mul_f32 v[52:53], v[10:11], v[68:69]
	v_cvt_pk_bf16_f32 v43, v50, v51
	v_pk_fma_f32 v[52:53], v[26:27], v[76:77], v[52:53]
	v_lshlrev_b32_e32 v50, 16, v44
	v_and_b32_e32 v51, 0xffff0000, v44
	v_pk_fma_f32 v[52:53], v[22:23], v[60:61], v[52:53]
	v_lshlrev_b32_e32 v48, 16, v49
	v_pk_mul_f32 v[50:51], v[52:53], v[50:51]
	v_pk_mul_f32 v[52:53], v[12:13], v[56:57]
	v_and_b32_e32 v49, 0xffff0000, v49
	v_pk_fma_f32 v[52:53], v[28:29], v[64:65], v[52:53]
	v_cvt_pk_bf16_f32 v44, v50, v51
	v_lshlrev_b32_e32 v50, 16, v45
	v_and_b32_e32 v51, 0xffff0000, v45
	v_pk_fma_f32 v[52:53], v[24:25], v[48:49], v[52:53]
	v_readlane_b32 s65, v196, 15
	v_pk_mul_f32 v[50:51], v[52:53], v[50:51]
	v_lshlrev_b32_e32 v52, 16, v20
	v_cvt_pk_bf16_f32 v45, v50, v51
	v_lshl_add_u64 v[50:51], s[68:69], 0, v[106:107]
	v_lshl_add_u64 v[50:51], v[50:51], 0, v[100:101]
	global_store_dwordx4 v[50:51], v[42:45], off sc1
	v_lshlrev_b32_e32 v50, 16, v18
	v_and_b32_e32 v51, 0xffff0000, v18
	v_pk_mul_f32 v[44:45], v[30:31], v[58:59]
	v_lshlrev_b32_e32 v42, 16, v14
	v_pk_fma_f32 v[44:45], v[38:39], v[66:67], v[44:45]
	v_and_b32_e32 v43, 0xffff0000, v14
	v_pk_fma_f32 v[44:45], v[34:35], v[50:51], v[44:45]
	v_lshlrev_b32_e32 v18, 16, v19
	v_pk_mul_f32 v[42:43], v[44:45], v[42:43]
	v_pk_mul_f32 v[44:45], v[32:33], v[46:47]
	v_and_b32_e32 v19, 0xffff0000, v19
	v_pk_fma_f32 v[44:45], v[40:41], v[54:55], v[44:45]
	v_cvt_pk_bf16_f32 v14, v42, v43
	v_lshlrev_b32_e32 v42, 16, v15
	v_and_b32_e32 v43, 0xffff0000, v15
	v_pk_fma_f32 v[44:45], v[36:37], v[18:19], v[44:45]
	v_and_b32_e32 v53, 0xffff0000, v20
	v_pk_mul_f32 v[42:43], v[44:45], v[42:43]
	v_pk_mul_f32 v[44:45], v[10:11], v[60:61]
	v_cvt_pk_bf16_f32 v15, v42, v43
	v_pk_fma_f32 v[44:45], v[26:27], v[68:69], v[44:45]
	v_lshlrev_b32_e32 v42, 16, v16
	v_and_b32_e32 v43, 0xffff0000, v16
	v_pk_fma_f32 v[44:45], v[22:23], v[52:53], v[44:45]
	v_lshlrev_b32_e32 v20, 16, v21
	v_pk_mul_f32 v[42:43], v[44:45], v[42:43]
	v_pk_mul_f32 v[44:45], v[12:13], v[48:49]
	v_and_b32_e32 v21, 0xffff0000, v21
	v_pk_fma_f32 v[44:45], v[28:29], v[56:57], v[44:45]
	v_cvt_pk_bf16_f32 v16, v42, v43
	v_lshlrev_b32_e32 v42, 16, v17
	v_and_b32_e32 v43, 0xffff0000, v17
	v_pk_fma_f32 v[44:45], v[24:25], v[20:21], v[44:45]
	v_pk_mul_f32 v[10:11], v[10:11], v[52:53]
	v_pk_mul_f32 v[42:43], v[44:45], v[42:43]
	v_pk_fma_f32 v[10:11], v[26:27], v[60:61], v[10:11]
	v_cvt_pk_bf16_f32 v17, v42, v43
	v_lshl_add_u64 v[42:43], s[68:69], 0, v[104:105]
	v_lshl_add_u64 v[42:43], v[42:43], 0, v[100:101]
	global_store_dwordx4 v[42:43], v[14:17], off sc1
	v_readlane_b32 s66, v196, 16
	v_readlane_b32 s67, v196, 17
	v_pk_mul_f32 v[16:17], v[30:31], v[50:51]
	v_lshlrev_b32_e32 v30, 16, v6
	v_pk_fma_f32 v[16:17], v[38:39], v[58:59], v[16:17]
	v_and_b32_e32 v31, 0xffff0000, v6
	v_lshlrev_b32_e32 v14, 16, v2
	v_and_b32_e32 v15, 0xffff0000, v2
	v_pk_fma_f32 v[16:17], v[34:35], v[30:31], v[16:17]
	v_lshlrev_b32_e32 v6, 16, v7
	v_pk_mul_f32 v[14:15], v[16:17], v[14:15]
	v_pk_mul_f32 v[16:17], v[32:33], v[18:19]
	v_and_b32_e32 v7, 0xffff0000, v7
	v_pk_fma_f32 v[16:17], v[40:41], v[46:47], v[16:17]
	v_cvt_pk_bf16_f32 v2, v14, v15
	v_lshlrev_b32_e32 v14, 16, v3
	v_and_b32_e32 v15, 0xffff0000, v3
	v_pk_fma_f32 v[6:7], v[36:37], v[6:7], v[16:17]
	v_readlane_b32 s70, v196, 20
	v_pk_mul_f32 v[6:7], v[6:7], v[14:15]
	v_lshlrev_b32_e32 v14, 16, v8
	v_and_b32_e32 v15, 0xffff0000, v8
	v_cvt_pk_bf16_f32 v3, v6, v7
	v_lshlrev_b32_e32 v6, 16, v4
	v_and_b32_e32 v7, 0xffff0000, v4
	v_pk_fma_f32 v[10:11], v[22:23], v[14:15], v[10:11]
	v_lshlrev_b32_e32 v8, 16, v9
	v_pk_mul_f32 v[6:7], v[10:11], v[6:7]
	v_pk_mul_f32 v[10:11], v[12:13], v[20:21]
	v_and_b32_e32 v9, 0xffff0000, v9
	v_pk_fma_f32 v[10:11], v[28:29], v[48:49], v[10:11]
	v_cvt_pk_bf16_f32 v4, v6, v7
	v_lshlrev_b32_e32 v6, 16, v5
	v_and_b32_e32 v7, 0xffff0000, v5
	v_pk_fma_f32 v[8:9], v[24:25], v[8:9], v[10:11]
	v_readlane_b32 s71, v196, 21
	v_pk_mul_f32 v[6:7], v[8:9], v[6:7]
	s_nop 0
	v_cvt_pk_bf16_f32 v5, v6, v7
	v_lshl_add_u64 v[6:7], s[68:69], 0, v[102:103]
	v_lshl_add_u64 v[6:7], v[6:7], 0, v[100:101]
	global_store_dwordx4 v[6:7], v[2:5], off sc1
	s_andn2_b64 exec, exec, s[10:11]
	s_cbranch_execz .LBB0_1109

.LBB0_1302:
	s_barrier
	s_waitcnt vmcnt(7)
	ds_write2_b32 v74, v2, v3 offset1:1
	ds_write2_b32 v74, v4, v5 offset0:2 offset1:3
	s_waitcnt vmcnt(6)
	ds_write2_b32 v74, v6, v7 offset0:4 offset1:5
	ds_write2_b32 v74, v8, v9 offset0:6 offset1:7
	v_add_u32_e32 v2, 0x4100, v74
	s_waitcnt vmcnt(5)
	ds_write2_b32 v2, v10, v11 offset1:1
	v_add_u32_e32 v2, 0x4108, v74
	ds_write2_b32 v2, v12, v13 offset1:1
	v_add_u32_e32 v2, 0x4110, v74
	s_waitcnt vmcnt(4)
	ds_write2_b32 v2, v14, v15 offset1:1
	v_add_u32_e32 v2, 0x4118, v74
	ds_write2_b32 v2, v16, v17 offset1:1
	v_add_u32_e32 v2, 0x8200, v74
	s_waitcnt vmcnt(3)
	ds_write2_b32 v2, v18, v19 offset1:1
	v_add_u32_e32 v2, 0x8208, v74
	ds_write2_b32 v2, v20, v21 offset1:1
	v_add_u32_e32 v2, 0x8210, v74
	s_waitcnt vmcnt(2)
	ds_write2_b32 v2, v22, v23 offset1:1
	v_add_u32_e32 v2, 0x8218, v74
	ds_write2_b32 v2, v24, v25 offset1:1
	v_add_u32_e32 v2, 0xc300, v74
	s_waitcnt vmcnt(1)
	ds_write2_b32 v2, v26, v27 offset1:1
	v_add_u32_e32 v2, 0xc308, v74
	ds_write2_b32 v2, v28, v29 offset1:1
	v_add_u32_e32 v2, 0xc310, v74
	s_waitcnt vmcnt(0)
	ds_write2_b32 v2, v30, v31 offset1:1
	v_add_u32_e32 v2, 0xc318, v74
	ds_write2_b32 v2, v32, v33 offset1:1
	s_waitcnt lgkmcnt(0)
	s_barrier
	ds_read2_b32 v[2:3], v75 offset1:65
	ds_read2_b32 v[4:5], v75 offset0:130 offset1:195
	v_add_u32_e32 v8, 0x400, v75
	ds_read2_b32 v[6:7], v8 offset0:4 offset1:69
	ds_read2_b32 v[8:9], v8 offset0:134 offset1:199
	v_add_u32_e32 v10, 0x4400, v75
	s_waitcnt lgkmcnt(3)
	v_cvt_pk_bf16_f32 v2, v2, v3
	s_waitcnt lgkmcnt(2)
	v_cvt_pk_bf16_f32 v3, v4, v5
	s_waitcnt lgkmcnt(1)
	v_cvt_pk_bf16_f32 v4, v6, v7
	v_add_u32_e32 v6, 0x4000, v75
	v_add_u32_e32 v12, 0x4600, v75
	s_waitcnt lgkmcnt(0)
	v_cvt_pk_bf16_f32 v5, v8, v9
	ds_read2_b32 v[6:7], v6 offset0:64 offset1:129
	v_add_u32_e32 v8, 0x4200, v75
	ds_read2_b32 v[10:11], v10 offset0:68 offset1:133
	ds_read2_b32 v[12:13], v12 offset0:70 offset1:135
	ds_read2_b32 v[8:9], v8 offset0:66 offset1:131
	global_store_dwordx4 v[70:71], v[2:5], off sc1
	s_cmpk_lt_i32 s23, 0x19d0
	s_mov_b32 s10, s23
	s_waitcnt lgkmcnt(3)
	v_cvt_pk_bf16_f32 v2, v6, v7
	s_waitcnt lgkmcnt(2)
	v_cvt_pk_bf16_f32 v4, v10, v11
	s_waitcnt lgkmcnt(1)
	v_cvt_pk_bf16_f32 v5, v12, v13
	v_add_u32_e32 v6, 0x8000, v75
	v_add_u32_e32 v10, 0x8400, v75
	v_add_u32_e32 v12, 0x8800, v75
	s_waitcnt lgkmcnt(0)
	v_cvt_pk_bf16_f32 v3, v8, v9
	ds_read2_b32 v[6:7], v6 offset0:128 offset1:193
	ds_read2_b32 v[8:9], v10 offset0:2 offset1:67
	ds_read2_b32 v[10:11], v10 offset0:132 offset1:197
	ds_read2_b32 v[12:13], v12 offset0:6 offset1:71
	global_store_dwordx4 v[70:71], v[2:5], off offset:128 sc1
	v_mov_b32_e32 v14, v42
	v_mov_b32_e32 v15, v43
	s_waitcnt lgkmcnt(3)
	v_cvt_pk_bf16_f32 v2, v6, v7
	s_waitcnt lgkmcnt(2)
	v_cvt_pk_bf16_f32 v3, v8, v9
	s_waitcnt lgkmcnt(1)
	v_cvt_pk_bf16_f32 v4, v10, v11
	s_waitcnt lgkmcnt(0)
	v_cvt_pk_bf16_f32 v5, v12, v13
	v_add_u32_e32 v6, 0xc200, v75
	v_add_u32_e32 v8, 0xc400, v75
	v_add_u32_e32 v10, 0xc600, v75
	v_add_u32_e32 v12, 0xc800, v75
	ds_read2_b32 v[6:7], v6 offset0:64 offset1:129
	ds_read2_b32 v[8:9], v8 offset0:66 offset1:131
	ds_read2_b32 v[10:11], v10 offset0:68 offset1:133
	ds_read2_b32 v[12:13], v12 offset0:70 offset1:135
	global_store_dwordx4 v[70:71], v[2:5], off offset:256 sc1
	v_mov_b32_e32 v16, v44
	v_mov_b32_e32 v17, v45
	s_waitcnt lgkmcnt(3)
	v_cvt_pk_bf16_f32 v2, v6, v7
	s_waitcnt lgkmcnt(2)
	v_cvt_pk_bf16_f32 v3, v8, v9
	s_waitcnt lgkmcnt(1)
	v_cvt_pk_bf16_f32 v4, v10, v11
	s_waitcnt lgkmcnt(0)
	v_cvt_pk_bf16_f32 v5, v12, v13
	global_store_dwordx4 v[70:71], v[2:5], off offset:384 sc1
	v_mov_b64_e32 v[70:71], v[72:73]
	v_mov_b32_e32 v6, v34
	v_mov_b32_e32 v2, v38
	v_mov_b32_e32 v3, v39
	v_mov_b32_e32 v4, v40
	v_mov_b32_e32 v5, v41
	v_mov_b32_e32 v7, v35
	v_mov_b32_e32 v8, v36
	v_mov_b32_e32 v9, v37
	v_mov_b32_e32 v10, v46
	v_mov_b32_e32 v11, v47
	v_mov_b32_e32 v12, v48
	v_mov_b32_e32 v13, v49
	v_mov_b32_e32 v18, v54
	v_mov_b32_e32 v19, v55
	v_mov_b32_e32 v20, v56
	v_mov_b32_e32 v21, v57
	v_mov_b32_e32 v22, v50
	v_mov_b32_e32 v23, v51
	v_mov_b32_e32 v24, v52
	v_mov_b32_e32 v25, v53
	v_mov_b32_e32 v26, v62
	v_mov_b32_e32 v27, v63
	v_mov_b32_e32 v28, v64
	v_mov_b32_e32 v29, v65
	v_mov_b32_e32 v30, v58
	v_mov_b32_e32 v31, v59
	v_mov_b32_e32 v32, v60
	v_mov_b32_e32 v33, v61
	s_cbranch_scc0 .LBB0_1325
